# C item: store-transpose barrier dropped (each wave reuses only the xhatT rows it alone reads); gate prefetch issued after the LayerNorm instead of in front of the later waves' xhat loads
# speedup vs baseline: 1.0290x; 1.0041x over previous
.LBB0_779:
	v_mov_b32_e32 v43, v0
	s_ashr_i32 s5, s3, 31
	v_ashrrev_i32_e32 v44, 7, v43
	s_waitcnt vmcnt(2)
	v_add_u32_e32 v164, s2, v44
	v_ashrrev_i32_e32 v165, 31, v164
	v_and_b32_e32 v168, 31, v43
	s_waitcnt vmcnt(0)
	v_lshlrev_b64 v[2:3], 15, v[164:165]
	v_bfe_u32 v169, v43, 5, 1
	v_lshl_add_u64 v[2:3], s[56:57], 0, v[2:3]
	v_and_b32_e32 v18, 63, v43
	v_lshlrev_b32_e32 v18, 4, v18
	v_lshlrev_b32_e32 v154, 4, v169
	v_add_u32_e32 v18, 0x1000, v18
	v_add_co_u32_e32 v18, vcc, v2, v18
	s_nop 1
	v_addc_co_u32_e32 v19, vcc, 0, v3, vcc
	v_add_co_u32_e32 v20, vcc, s14, v18
	v_ashrrev_i32_e32 v45, 2, v43
	s_nop 0
	v_addc_co_u32_e32 v21, vcc, 0, v19, vcc
	v_add_co_u32_e32 v22, vcc, s17, v18
	global_load_dwordx4 v[2:5], v[18:19], off offset:-4096
	global_load_dwordx4 v[6:9], v[20:21], off offset:-4096
	v_addc_co_u32_e32 v23, vcc, 0, v19, vcc
	v_add_co_u32_e32 v24, vcc, s30, v18
	global_load_dwordx4 v[10:13], v[22:23], off offset:-4096
	s_nop 0
	v_addc_co_u32_e32 v25, vcc, 0, v19, vcc
	global_load_dwordx4 v[14:17], v[24:25], off offset:-4096
	global_load_dwordx4 v[138:141], v[18:19], off offset:-3072
	global_load_dwordx4 v[142:145], v[20:21], off offset:-3072
	global_load_dwordx4 v[146:149], v[22:23], off offset:-3072
	global_load_dwordx4 v[150:153], v[24:25], off offset:-3072
	global_load_dwordx4 v[126:129], v[20:21], off offset:-2048
	global_load_dwordx4 v[130:133], v[22:23], off offset:-2048
	global_load_dwordx4 v[134:137], v[24:25], off offset:-2048
	global_load_dwordx4 v[114:117], v[20:21], off offset:-1024
	global_load_dwordx4 v[118:121], v[22:23], off offset:-1024
	global_load_dwordx4 v[122:125], v[24:25], off offset:-1024
	global_load_dwordx4 v[106:109], v[22:23], off
	global_load_dwordx4 v[110:113], v[24:25], off
	global_load_dwordx4 v[98:101], v[22:23], off offset:1024
	global_load_dwordx4 v[102:105], v[24:25], off offset:1024
	global_load_dwordx4 v[94:97], v[24:25], off offset:2048
	global_load_dwordx4 v[90:93], v[24:25], off offset:3072
	v_add_u32_e32 v18, s3, v45
	v_ashrrev_i32_e32 v19, 31, v18
	v_lshlrev_b32_e32 v20, 6, v43
	v_lshlrev_b64 v[18:19], 12, v[18:19]
	v_and_b32_e32 v46, 0xc0, v20
	v_lshl_add_u64 v[18:19], s[60:61], 0, v[18:19]
	v_lshlrev_b32_e32 v20, 1, v46
	v_mov_b32_e32 v21, v155
	v_lshl_add_u64 v[34:35], v[18:19], 0, v[20:21]
	global_load_dwordx4 v[18:21], v[34:35], off offset:3632
	global_load_dwordx4 v[22:25], v[34:35], off offset:3616
	global_load_dwordx4 v[26:29], v[34:35], off offset:3600
	global_load_dwordx4 v[30:33], v[34:35], off offset:3584
	global_load_dwordx4 v[36:39], v[34:35], off offset:3680
	global_load_dwordx4 v[202:205], v[34:35], off offset:3664
	global_load_dwordx4 v[48:51], v[34:35], off offset:3648
	global_load_dwordx4 v[206:209], v[34:35], off offset:3696
	v_lshrrev_b32_e32 v42, 5, v43
	s_add_i32 s4, s4, s46
	s_waitcnt vmcnt(7)
	v_lshlrev_b32_e32 v178, 16, v18
	s_waitcnt vmcnt(6)
	v_lshlrev_b32_e32 v186, 16, v22
	s_waitcnt vmcnt(5)
	v_lshlrev_b32_e32 v194, 16, v26
	s_waitcnt vmcnt(4)
	v_lshlrev_b32_e32 v200, 16, v30
	v_and_b32_e32 v199, 0xffff0000, v30
	v_add_f32_e32 v30, 0, v200
	v_lshlrev_b32_e32 v198, 16, v31
	v_add_f32_e32 v30, v30, v199
	v_and_b32_e32 v197, 0xffff0000, v31
	v_mul_f32_e32 v31, v199, v199
	v_add_f32_e32 v30, v30, v198
	v_lshlrev_b32_e32 v196, 16, v32
	v_fmac_f32_e32 v31, v200, v200
	v_add_f32_e32 v30, v30, v197
	v_and_b32_e32 v195, 0xffff0000, v32
	v_fmac_f32_e32 v31, v198, v198
	v_add_f32_e32 v30, v30, v196
	v_lshlrev_b32_e32 v193, 16, v33
	v_fmac_f32_e32 v31, v197, v197
	v_add_f32_e32 v30, v30, v195
	v_and_b32_e32 v191, 0xffff0000, v33
	v_fmac_f32_e32 v31, v196, v196
	v_add_f32_e32 v30, v30, v193
	v_fmac_f32_e32 v31, v195, v195
	v_add_f32_e32 v30, v30, v191
	v_fmac_f32_e32 v31, v193, v193
	v_and_b32_e32 v192, 0xffff0000, v26
	v_add_f32_e32 v26, v30, v194
	v_fmac_f32_e32 v31, v191, v191
	v_lshlrev_b32_e32 v190, 16, v27
	v_add_f32_e32 v26, v26, v192
	v_and_b32_e32 v189, 0xffff0000, v27
	v_fmac_f32_e32 v31, v194, v194
	v_add_f32_e32 v26, v26, v190
	v_lshlrev_b32_e32 v188, 16, v28
	v_fmac_f32_e32 v31, v192, v192
	v_add_f32_e32 v26, v26, v189
	v_and_b32_e32 v187, 0xffff0000, v28
	v_fmac_f32_e32 v31, v190, v190
	v_add_f32_e32 v26, v26, v188
	v_lshlrev_b32_e32 v184, 16, v29
	v_fmac_f32_e32 v31, v189, v189
	v_add_f32_e32 v26, v26, v187
	v_and_b32_e32 v182, 0xffff0000, v29
	v_fmac_f32_e32 v31, v188, v188
	v_add_f32_e32 v26, v26, v184
	v_fmac_f32_e32 v31, v187, v187
	v_add_f32_e32 v26, v26, v182
	v_fmac_f32_e32 v31, v184, v184
	v_and_b32_e32 v185, 0xffff0000, v22
	v_add_f32_e32 v22, v26, v186
	v_fmac_f32_e32 v31, v182, v182
	v_lshlrev_b32_e32 v183, 16, v23
	v_add_f32_e32 v22, v22, v185
	v_and_b32_e32 v179, 0xffff0000, v23
	v_fmac_f32_e32 v31, v186, v186
	v_add_f32_e32 v22, v22, v183
	v_lshlrev_b32_e32 v177, 16, v24
	v_fmac_f32_e32 v31, v185, v185
	v_add_f32_e32 v22, v22, v179
	v_and_b32_e32 v175, 0xffff0000, v24
	v_fmac_f32_e32 v31, v183, v183
	v_add_f32_e32 v22, v22, v177
	v_lshlrev_b32_e32 v173, 16, v25
	v_fmac_f32_e32 v31, v179, v179
	v_add_f32_e32 v22, v22, v175
	v_and_b32_e32 v171, 0xffff0000, v25
	v_fmac_f32_e32 v31, v177, v177
	v_add_f32_e32 v22, v22, v173
	v_fmac_f32_e32 v31, v175, v175
	v_add_f32_e32 v22, v22, v171
	v_fmac_f32_e32 v31, v173, v173
	v_and_b32_e32 v176, 0xffff0000, v18
	v_add_f32_e32 v18, v22, v178
	v_fmac_f32_e32 v31, v171, v171
	v_lshlrev_b32_e32 v174, 16, v19
	v_add_f32_e32 v18, v18, v176
	v_and_b32_e32 v172, 0xffff0000, v19
	v_fmac_f32_e32 v31, v178, v178
	v_add_f32_e32 v18, v18, v174
	v_lshlrev_b32_e32 v167, 16, v20
	v_fmac_f32_e32 v31, v176, v176
	v_add_f32_e32 v18, v18, v172
	v_and_b32_e32 v165, 0xffff0000, v20
	v_fmac_f32_e32 v31, v174, v174
	v_add_f32_e32 v18, v18, v167
	v_lshlrev_b32_e32 v64, 16, v21
	v_fmac_f32_e32 v31, v172, v172
	v_add_f32_e32 v18, v18, v165
	v_and_b32_e32 v62, 0xffff0000, v21
	v_fmac_f32_e32 v31, v167, v167
	v_add_f32_e32 v18, v18, v64
	v_fmac_f32_e32 v31, v165, v165
	v_add_f32_e32 v18, v18, v62
	s_waitcnt vmcnt(1)
	v_lshlrev_b32_e32 v170, 16, v48
	v_fmac_f32_e32 v31, v64, v64
	v_and_b32_e32 v166, 0xffff0000, v48
	v_add_f32_e32 v18, v18, v170
	v_fmac_f32_e32 v31, v62, v62
	v_lshlrev_b32_e32 v65, 16, v49
	v_add_f32_e32 v18, v18, v166
	v_and_b32_e32 v63, 0xffff0000, v49
	v_fmac_f32_e32 v31, v170, v170
	v_add_f32_e32 v18, v18, v65
	v_lshlrev_b32_e32 v60, 16, v50
	v_fmac_f32_e32 v31, v166, v166
	v_add_f32_e32 v18, v18, v63
	v_and_b32_e32 v59, 0xffff0000, v50
	v_fmac_f32_e32 v31, v65, v65
	v_add_f32_e32 v18, v18, v60
	v_lshlrev_b32_e32 v57, 16, v51
	v_fmac_f32_e32 v31, v63, v63
	v_add_f32_e32 v18, v18, v59
	v_and_b32_e32 v55, 0xffff0000, v51
	v_fmac_f32_e32 v31, v60, v60
	v_add_f32_e32 v18, v18, v57
	v_fmac_f32_e32 v31, v59, v59
	v_add_f32_e32 v18, v18, v55
	v_lshlrev_b32_e32 v61, 16, v202
	v_fmac_f32_e32 v31, v57, v57
	v_and_b32_e32 v58, 0xffff0000, v202
	v_add_f32_e32 v18, v18, v61
	v_fmac_f32_e32 v31, v55, v55
	v_lshlrev_b32_e32 v56, 16, v203
	v_add_f32_e32 v18, v18, v58
	v_and_b32_e32 v54, 0xffff0000, v203
	v_fmac_f32_e32 v31, v61, v61
	v_add_f32_e32 v18, v18, v56
	v_lshlrev_b32_e32 v53, 16, v204
	v_fmac_f32_e32 v31, v58, v58
	v_add_f32_e32 v18, v18, v54
	v_and_b32_e32 v51, 0xffff0000, v204
	v_fmac_f32_e32 v31, v56, v56
	v_add_f32_e32 v18, v18, v53
	v_lshlrev_b32_e32 v49, 16, v205
	v_fmac_f32_e32 v31, v54, v54
	v_add_f32_e32 v18, v18, v51
	v_and_b32_e32 v47, 0xffff0000, v205
	v_fmac_f32_e32 v31, v53, v53
	v_add_f32_e32 v18, v18, v49
	v_fmac_f32_e32 v31, v51, v51
	v_add_f32_e32 v18, v18, v47
	v_lshlrev_b32_e32 v52, 16, v36
	v_fmac_f32_e32 v31, v49, v49
	v_and_b32_e32 v50, 0xffff0000, v36
	v_add_f32_e32 v18, v18, v52
	v_fmac_f32_e32 v31, v47, v47
	v_lshlrev_b32_e32 v48, 16, v37
	v_add_f32_e32 v18, v18, v50
	v_fmac_f32_e32 v31, v52, v52
	v_add_f32_e32 v18, v18, v48
	v_and_b32_e32 v37, 0xffff0000, v37
	v_fmac_f32_e32 v31, v50, v50
	v_lshlrev_b32_e32 v34, 16, v38
	v_mov_b32_e32 v35, v37
	v_add_f32_e32 v20, v18, v37
	v_fmac_f32_e32 v31, v48, v48
	v_and_b32_e32 v24, 0xffff0000, v38
	v_pk_mul_f32 v[18:19], v[34:35], v[34:35]
	v_add_f32_e32 v20, v20, v34
	v_lshlrev_b32_e32 v25, 16, v39
	v_add_f32_e32 v19, v19, v31
	v_add_f32_e32 v20, v20, v24
	v_add_f32_e32 v21, v18, v19
	v_pk_mul_f32 v[18:19], v[24:25], v[24:25]
	v_add_f32_e32 v20, v20, v25
	v_and_b32_e32 v33, 0xffff0000, v39
	v_add_f32_e32 v18, v18, v21
	s_waitcnt vmcnt(0)
	v_lshlrev_b32_e32 v28, 16, v206
	v_mov_b32_e32 v29, v33
	v_add_f32_e32 v20, v20, v33
	v_add_f32_e32 v21, v19, v18
	v_and_b32_e32 v22, 0xffff0000, v206
	v_pk_mul_f32 v[18:19], v[28:29], v[28:29]
	v_add_f32_e32 v20, v20, v28
	v_lshlrev_b32_e32 v23, 16, v207
	v_add_f32_e32 v19, v19, v21
	v_add_f32_e32 v20, v20, v22
	v_add_f32_e32 v21, v18, v19
	v_pk_mul_f32 v[18:19], v[22:23], v[22:23]
	v_add_f32_e32 v29, v20, v23
	v_and_b32_e32 v31, 0xffff0000, v207
	v_add_f32_e32 v18, v18, v21
	v_lshlrev_b32_e32 v26, 16, v208
	v_mov_b32_e32 v27, v31
	v_add_f32_e32 v29, v29, v31
	v_and_b32_e32 v36, s0, v38
	v_add_f32_e32 v18, v19, v18
	v_and_b32_e32 v20, 0xffff0000, v208
	v_pk_mul_f32 v[38:39], v[26:27], v[26:27]
	v_add_f32_e32 v27, v29, v26
	v_lshlrev_b32_e32 v21, 16, v209
	v_add_f32_e32 v18, v39, v18
	v_add_f32_e32 v27, v27, v20
	v_and_b32_e32 v29, 64, v181
	v_add_f32_e32 v18, v38, v18
	v_pk_mul_f32 v[40:41], v[20:21], v[20:21]
	v_add_f32_e32 v39, v27, v21
	v_xor_b32_e32 v27, 1, v181
	v_add_u32_e32 v29, 64, v29
	v_and_b32_e32 v19, 0xffff0000, v209
	v_add_f32_e32 v18, v40, v18
	v_cmp_lt_i32_e32 vcc, v27, v29
	v_add_f32_e32 v18, v41, v18
	v_mul_f32_e32 v38, v19, v19
	v_cndmask_b32_e32 v27, v181, v27, vcc
	v_lshlrev_b32_e32 v27, 2, v27
	v_pk_add_f32 v[38:39], v[38:39], v[18:19]
	ds_bpermute_b32 v41, v27, v39
	ds_bpermute_b32 v40, v27, v38
	v_xor_b32_e32 v35, 2, v181
	v_cmp_lt_i32_e32 vcc, v35, v29
	v_and_b32_e32 v30, s0, v206
	v_mov_b32_e32 v32, v36
	v_cndmask_b32_e32 v29, v181, v35, vcc
	v_lshlrev_b32_e32 v29, 2, v29
	s_waitcnt lgkmcnt(0)
	v_pk_add_f32 v[38:39], v[38:39], v[40:41]
	ds_bpermute_b32 v41, v29, v39
	ds_bpermute_b32 v40, v29, v38
	s_waitcnt lgkmcnt(0)
	v_pk_add_f32 v[40:41], v[38:39], v[40:41]
	s_nop 0
	v_pk_mul_f32 v[38:39], v[40:41], s[22:23] op_sel_hi:[1,0]
	v_pk_fma_f32 v[36:37], v[40:41], s[22:23], v[36:37] op_sel_hi:[1,0,1] neg_lo:[1,0,0] neg_hi:[1,0,0]
	v_fma_f32 v18, -v39, v39, v38
	v_max_f32_e32 v18, 0, v18
	v_add_f32_e32 v18, 0x358637bd, v18
	v_cmp_gt_f32_e32 vcc, s33, v18
	v_mul_f32_e32 v27, 0x4b800000, v18
	v_sub_f32_e32 v29, v200, v39
	v_cndmask_b32_e32 v18, v18, v27, vcc
	v_rsq_f32_e32 v18, v18
	v_sub_f32_e32 v19, v19, v39
	v_mul_f32_e32 v27, 0x45800000, v18
	v_cndmask_b32_e32 v18, v18, v27, vcc
	v_mul_f32_e32 v29, v29, v18
	v_lshlrev_b32_e32 v27, 1, v45
	v_bfe_u32 v35, v29, 16, 1
	v_ashrrev_i32_e32 v45, 1, v43
	v_and_b32_e32 v27, 14, v27
	v_add3_u32 v29, v29, v35, s15
	v_lshl_add_u32 v35, v46, 8, 32
	v_and_b32_e32 v46, -16, v45
	v_add3_u32 v200, v35, v46, v27
	ds_write_b16_d16_hi v200, v29 offset:55296
	v_mul_f32_e64 v215, -v39, v18
	v_fma_f32 v29, v199, v18, v215
	v_cvt_pk_bf16_f32 v29, v29, v29
	v_bitop3_b32 v199, v45, 16, -16 bitop3:0x6c
	v_add3_u32 v201, v35, v199, v27
	ds_write_b16 v201, v29 offset:55552
	v_fma_f32 v29, v198, v18, v215
	v_cvt_pk_bf16_f32 v29, v29, v29
	v_bitop3_b32 v198, v45, 32, -16 bitop3:0x6c
	v_add3_u32 v202, v35, v198, v27
	ds_write_b16 v202, v29 offset:55808
	v_fma_f32 v29, v197, v18, v215
	v_cvt_pk_bf16_f32 v29, v29, v29
	v_bitop3_b32 v197, v45, 48, -16 bitop3:0x6c
	v_add3_u32 v203, v35, v197, v27
	ds_write_b16 v203, v29 offset:56064
	v_fma_f32 v29, v196, v18, v215
	v_cvt_pk_bf16_f32 v29, v29, v29
	v_bitop3_b32 v196, v45, 64, -16 bitop3:0x6c
	v_add3_u32 v204, v35, v196, v27
	ds_write_b16 v204, v29 offset:56320
	v_fma_f32 v29, v195, v18, v215
	v_cvt_pk_bf16_f32 v29, v29, v29
	v_bitop3_b32 v195, v45, s34, -16 bitop3:0x6c
	v_add3_u32 v205, v35, v195, v27
	ds_write_b16 v205, v29 offset:56576
	v_fma_f32 v29, v193, v18, v215
	v_cvt_pk_bf16_f32 v29, v29, v29
	v_bitop3_b32 v193, v45, s31, -16 bitop3:0x6c
	v_add3_u32 v206, v35, v193, v27
	ds_write_b16 v206, v29 offset:56832
	v_fma_f32 v29, v191, v18, v215
	v_cvt_pk_bf16_f32 v29, v29, v29
	v_bitop3_b32 v191, v45, s13, -16 bitop3:0x6c
	v_add3_u32 v207, v35, v191, v27
	ds_write_b16 v207, v29 offset:57088
	v_fma_f32 v29, v194, v18, v215
	v_cvt_pk_bf16_f32 v29, v29, v29
	v_bitop3_b32 v194, v45, s12, -16 bitop3:0x6c
	v_add3_u32 v208, v35, v194, v27
	ds_write_b16 v208, v29 offset:57344
	v_fma_f32 v29, v192, v18, v215
	v_cvt_pk_bf16_f32 v29, v29, v29
	v_bitop3_b32 v192, v45, s35, -16 bitop3:0x6c
	v_add3_u32 v209, v35, v192, v27
	ds_write_b16 v209, v29 offset:57600
	v_fma_f32 v29, v190, v18, v215
	v_cvt_pk_bf16_f32 v29, v29, v29
	v_bitop3_b32 v190, v45, s36, -16 bitop3:0x6c
	v_add3_u32 v210, v35, v190, v27
	ds_write_b16 v210, v29 offset:57856
	v_fma_f32 v29, v189, v18, v215
	v_cvt_pk_bf16_f32 v29, v29, v29
	v_bitop3_b32 v189, v45, s37, -16 bitop3:0x6c
	v_add3_u32 v211, v35, v189, v27
	ds_write_b16 v211, v29 offset:58112
	v_fma_f32 v29, v188, v18, v215
	v_cvt_pk_bf16_f32 v29, v29, v29
	v_bitop3_b32 v188, v45, s16, -16 bitop3:0x6c
	v_add3_u32 v212, v35, v188, v27
	ds_write_b16 v212, v29 offset:58368
	v_fma_f32 v29, v187, v18, v215
	v_cvt_pk_bf16_f32 v29, v29, v29
	v_bitop3_b32 v187, v45, s42, -16 bitop3:0x6c
	v_add3_u32 v213, v35, v187, v27
	ds_write_b16 v213, v29 offset:58624
	v_fma_f32 v29, v184, v18, v215
	v_cvt_pk_bf16_f32 v29, v29, v29
	v_bitop3_b32 v184, v45, s43, -16 bitop3:0x6c
	v_add3_u32 v214, v35, v184, v27
	ds_write_b16 v214, v29 offset:58880
	v_sub_f32_e32 v29, v182, v39
	v_mul_f32_e32 v29, v29, v18
	v_bfe_u32 v182, v29, 16, 1
	v_bitop3_b32 v45, v45, s94, -16 bitop3:0x6c
	v_add_u32_e32 v38, 0xd800, v35
	v_add3_u32 v29, v29, v182, s15
	v_add3_u32 v35, v35, v45, v27
	ds_write_b16_d16_hi v35, v29 offset:59136
	v_fma_f32 v29, v186, v18, v215
	v_cvt_pk_bf16_f32 v29, v29, v29
	ds_write_b16 v200, v29 offset:59392
	v_fma_f32 v29, v185, v18, v215
	v_cvt_pk_bf16_f32 v29, v29, v29
	ds_write_b16 v201, v29 offset:59648
	v_fma_f32 v29, v183, v18, v215
	v_cvt_pk_bf16_f32 v29, v29, v29
	ds_write_b16 v202, v29 offset:59904
	v_fma_f32 v29, v179, v18, v215
	v_cvt_pk_bf16_f32 v29, v29, v29
	ds_write_b16 v203, v29 offset:60160
	v_fma_f32 v29, v177, v18, v215
	v_cvt_pk_bf16_f32 v29, v29, v29
	ds_write_b16 v204, v29 offset:60416
	v_fma_f32 v29, v175, v18, v215
	v_cvt_pk_bf16_f32 v29, v29, v29
	ds_write_b16 v205, v29 offset:60672
	v_fma_f32 v29, v173, v18, v215
	v_cvt_pk_bf16_f32 v29, v29, v29
	ds_write_b16 v206, v29 offset:60928
	v_fma_f32 v29, v171, v18, v215
	v_cvt_pk_bf16_f32 v29, v29, v29
	ds_write_b16 v207, v29 offset:61184
	v_fma_f32 v29, v178, v18, v215
	v_cvt_pk_bf16_f32 v29, v29, v29
	ds_write_b16 v208, v29 offset:61440
	v_fma_f32 v29, v176, v18, v215
	v_cvt_pk_bf16_f32 v29, v29, v29
	ds_write_b16 v209, v29 offset:61696
	v_fma_f32 v29, v174, v18, v215
	v_cvt_pk_bf16_f32 v29, v29, v29
	ds_write_b16 v210, v29 offset:61952
	v_fma_f32 v29, v172, v18, v215
	v_cvt_pk_bf16_f32 v29, v29, v29
	ds_write_b16 v211, v29 offset:62208
	v_fma_f32 v29, v167, v18, v215
	v_cvt_pk_bf16_f32 v29, v29, v29
	ds_write_b16 v212, v29 offset:62464
	v_fma_f32 v29, v165, v18, v215
	v_cvt_pk_bf16_f32 v29, v29, v29
	ds_write_b16 v213, v29 offset:62720
	v_fma_f32 v29, v64, v18, v215
	v_cvt_pk_bf16_f32 v29, v29, v29
	ds_write_b16 v214, v29 offset:62976
	v_fma_f32 v29, v62, v18, v215
	v_cvt_pk_bf16_f32 v29, v29, v29
	ds_write_b16 v35, v29 offset:63232
	v_fma_f32 v29, v170, v18, v215
	v_cvt_pk_bf16_f32 v29, v29, v29
	ds_write_b16 v200, v29 offset:63488
	v_fma_f32 v29, v166, v18, v215
	v_cvt_pk_bf16_f32 v29, v29, v29
	ds_write_b16 v201, v29 offset:63744
	v_fma_f32 v29, v65, v18, v215
	v_cvt_pk_bf16_f32 v29, v29, v29
	ds_write_b16 v202, v29 offset:64000
	v_fma_f32 v29, v63, v18, v215
	v_cvt_pk_bf16_f32 v29, v29, v29
	ds_write_b16 v203, v29 offset:64256
	v_fma_f32 v29, v60, v18, v215
	v_cvt_pk_bf16_f32 v29, v29, v29
	ds_write_b16 v204, v29 offset:64512
	v_fma_f32 v29, v59, v18, v215
	v_cvt_pk_bf16_f32 v29, v29, v29
	ds_write_b16 v205, v29 offset:64768
	v_fma_f32 v29, v57, v18, v215
	v_cvt_pk_bf16_f32 v29, v29, v29
	ds_write_b16 v206, v29 offset:65024
	v_fma_f32 v29, v55, v18, v215
	v_cvt_pk_bf16_f32 v29, v29, v29
	ds_write_b16 v207, v29 offset:65280
	v_fma_f32 v29, v61, v18, v215
	v_cvt_pk_bf16_f32 v29, v29, v29
	v_add3_u32 v35, v38, v194, v27
	ds_write_b16 v35, v29 offset:10240
	v_fma_f32 v29, v58, v18, v215
	v_cvt_pk_bf16_f32 v29, v29, v29
	v_add3_u32 v55, v38, v192, v27
	ds_write_b16 v55, v29 offset:10496
	v_fma_f32 v29, v56, v18, v215
	v_cvt_pk_bf16_f32 v29, v29, v29
	v_add3_u32 v56, v38, v190, v27
	ds_write_b16 v56, v29 offset:10752
	v_fma_f32 v29, v54, v18, v215
	v_cvt_pk_bf16_f32 v29, v29, v29
	v_add3_u32 v54, v38, v189, v27
	ds_write_b16 v54, v29 offset:11008
	v_fma_f32 v29, v53, v18, v215
	v_cvt_pk_bf16_f32 v29, v29, v29
	v_add3_u32 v53, v38, v188, v27
	ds_write_b16 v53, v29 offset:11264
	v_fma_f32 v29, v51, v18, v215
	v_cvt_pk_bf16_f32 v29, v29, v29
	v_add3_u32 v51, v38, v187, v27
	ds_write_b16 v51, v29 offset:11520
	v_fma_f32 v29, v49, v18, v215
	v_cvt_pk_bf16_f32 v29, v29, v29
	v_add3_u32 v49, v38, v184, v27
	ds_write_b16 v49, v29 offset:11776
	v_fma_f32 v29, v47, v18, v215
	v_cvt_pk_bf16_f32 v29, v29, v29
	v_add3_u32 v45, v38, v45, v27
	ds_write_b16 v45, v29 offset:12032
	v_fma_f32 v29, v52, v18, v215
	v_cvt_pk_bf16_f32 v29, v29, v29
	v_add3_u32 v46, v38, v46, v27
	ds_write_b16 v46, v29 offset:12288
	v_fma_f32 v29, v50, v18, v215
	v_cvt_pk_bf16_f32 v29, v29, v29
	v_add3_u32 v46, v38, v199, v27
	ds_write_b16 v46, v29 offset:12544
	v_fma_f32 v29, v48, v18, v215
	v_cvt_pk_bf16_f32 v29, v29, v29
	v_add3_u32 v46, v38, v198, v27
	ds_write_b16 v46, v29 offset:12800
	v_mul_f32_e32 v29, v37, v18
	v_bfe_u32 v36, v29, 16, 1
	v_add3_u32 v29, v29, v36, s15
	v_add3_u32 v36, v38, v197, v27
	ds_write_b16_d16_hi v36, v29 offset:13056
	v_fma_f32 v29, v34, v18, v215
	v_cvt_pk_bf16_f32 v29, v29, v29
	v_add3_u32 v34, v38, v196, v27
	ds_write_b16 v34, v29 offset:13312
	v_sub_f32_e32 v29, v24, v39
	v_pk_fma_f32 v[24:25], v[40:41], s[22:23], v[24:25] op_sel_hi:[1,0,1] neg_lo:[1,0,0] neg_hi:[1,0,0]
	v_mul_f32_e32 v29, v29, v18
	v_mul_f32_e32 v24, v25, v18
	v_bfe_u32 v34, v29, 16, 1
	v_bfe_u32 v25, v24, 16, 1
	v_add3_u32 v29, v29, v34, s15
	v_add3_u32 v34, v38, v195, v27
	v_add3_u32 v24, v24, v25, s15
	v_add3_u32 v25, v38, v193, v27
	ds_write_b16_d16_hi v34, v29 offset:13568
	ds_write_b16_d16_hi v25, v24 offset:13824
	v_pk_fma_f32 v[24:25], v[40:41], s[22:23], v[32:33] op_sel_hi:[1,0,1] neg_lo:[1,0,0] neg_hi:[1,0,0]
	v_and_b32_e32 v167, 15, v43
	v_mul_f32_e32 v24, v25, v18
	v_bfe_u32 v25, v24, 16, 1
	v_add3_u32 v24, v24, v25, s15
	v_add3_u32 v25, v38, v191, v27
	ds_write_b16_d16_hi v25, v24 offset:14080
	v_fma_f32 v24, v28, v18, v215
	v_cvt_pk_bf16_f32 v24, v24, v24
	ds_write_b16 v35, v24 offset:14336
	v_sub_f32_e32 v24, v22, v39
	v_pk_fma_f32 v[22:23], v[40:41], s[22:23], v[22:23] op_sel_hi:[1,0,1] neg_lo:[1,0,0] neg_hi:[1,0,0]
	v_mul_f32_e32 v24, v24, v18
	v_mul_f32_e32 v22, v23, v18
	v_bfe_u32 v25, v24, 16, 1
	v_bfe_u32 v23, v22, 16, 1
	v_add3_u32 v24, v24, v25, s15
	v_add3_u32 v22, v22, v23, s15
	ds_write_b16_d16_hi v55, v24 offset:14592
	ds_write_b16_d16_hi v56, v22 offset:14848
	v_pk_fma_f32 v[22:23], v[40:41], s[22:23], v[30:31] op_sel_hi:[1,0,1] neg_lo:[1,0,0] neg_hi:[1,0,0]
	s_nop 0
	v_mul_f32_e32 v22, v23, v18
	v_bfe_u32 v23, v22, 16, 1
	v_add3_u32 v22, v22, v23, s15
	ds_write_b16_d16_hi v54, v22 offset:15104
	v_fma_f32 v22, v26, v18, v215
	v_cvt_pk_bf16_f32 v22, v22, v22
	ds_write_b16 v53, v22 offset:15360
	v_sub_f32_e32 v22, v20, v39
	v_pk_fma_f32 v[20:21], v[40:41], s[22:23], v[20:21] op_sel_hi:[1,0,1] neg_lo:[1,0,0] neg_hi:[1,0,0]
	v_mul_f32_e32 v22, v22, v18
	v_mul_f32_e32 v20, v21, v18
	v_mul_f32_e32 v18, v19, v18
	v_bfe_u32 v23, v22, 16, 1
	v_bfe_u32 v21, v20, 16, 1
	v_bfe_u32 v19, v18, 16, 1
	v_add3_u32 v22, v22, v23, s15
	v_add3_u32 v20, v20, v21, s15
	v_add3_u32 v18, v18, v19, s15
	ds_write_b16_d16_hi v51, v22 offset:15616
	ds_write_b16_d16_hi v49, v20 offset:15872
	ds_write_b16_d16_hi v45, v18 offset:16128
	v_lshrrev_b32_e32 v18, 1, v43
	v_and_b32_e32 v18, 32, v18
	v_lshl_or_b32 v166, v44, 6, v18
	v_or_b32_e32 v18, v166, v168
	v_lshl_add_u32 v165, v18, 8, 32
	v_bitop3_b32 v18, v42, v167, 1 bitop3:0x6c
	v_lshl_add_u32 v18, v18, 4, v165
	v_and_b32_e32 v215, 31, v0
	v_add_u32_e32 v215, s3, v215
	v_lshlrev_b32_e32 v215, 12, v215
	v_and_b32_e32 v245, 0x1c0, v0
	v_add_u32_e32 v215, v215, v245
	v_bfe_u32 v245, v0, 5, 1
	v_lshl_add_u32 v245, v245, 3, v215
	v_bfe_u32 v215, v0, 5, 1
	v_lshl_add_u32 v215, v215, 3, v245
	global_load_dwordx4 v[216:219], v215, s[60:61] offset:3072
	global_load_dwordx4 v[220:223], v215, s[60:61] offset:3104
	s_add_u32 s98, s60, 0x20000
	s_addc_u32 s99, s61, 0
	global_load_dwordx4 v[224:227], v215, s[98:99] offset:3072
	global_load_dwordx4 v[228:231], v215, s[98:99] offset:3104
	s_add_u32 s100, s60, 0x40000
	s_addc_u32 s101, s61, 0
	global_load_dwordx4 v[232:235], v215, s[100:101] offset:3072
	global_load_dwordx4 v[236:239], v215, s[100:101] offset:3104
	s_add_u32 s98, s60, 0x60000
	s_addc_u32 s99, s61, 0
	global_load_dwordx4 v[252:255], v215, s[98:99] offset:3072
	global_load_dwordx2 v[240:241], v245, s[98:99] offset:3104
	global_load_dwordx2 v[246:247], v245, s[98:99] offset:3120
	s_waitcnt lgkmcnt(0)
	s_barrier
	ds_read_b128 v[170:173], v18 offset:55296
	s_waitcnt lgkmcnt(0)
	v_mfma_f32_32x32x16_bf16 v[50:65], v[170:173], v[2:5], 0
	v_mfma_f32_32x32x16_bf16 v[34:49], v[170:173], v[6:9], 0
	v_mfma_f32_32x32x16_bf16 v[18:33], v[170:173], v[10:13], 0
	v_mfma_f32_32x32x16_bf16 v[2:17], v[170:173], v[14:17], 0
	v_bitop3_b32 v170, v169, v167, 2 bitop3:0x36
	v_lshl_add_u32 v170, v170, 4, v165
	ds_read_b128 v[170:173], v170 offset:55296
	s_waitcnt lgkmcnt(0)
	v_mfma_f32_32x32x16_bf16 v[50:65], v[170:173], v[138:141], v[50:65]
	v_bitop3_b32 v138, v169, v167, 4 bitop3:0x36
	v_lshl_add_u32 v138, v138, 4, v165
	ds_read_b128 v[138:141], v138 offset:55296
	v_mfma_f32_32x32x16_bf16 v[34:49], v[170:173], v[142:145], v[34:49]
	v_mfma_f32_32x32x16_bf16 v[18:33], v[170:173], v[146:149], v[18:33]
	s_waitcnt lgkmcnt(0)
	v_mfma_f32_32x32x16_bf16 v[34:49], v[138:141], v[126:129], v[34:49]
	v_bitop3_b32 v126, v169, v167, 6 bitop3:0x36
	v_lshl_add_u32 v126, v126, 4, v165
	ds_read_b128 v[126:129], v126 offset:55296
	v_mfma_f32_32x32x16_bf16 v[2:17], v[170:173], v[150:153], v[2:17]
	v_mfma_f32_32x32x16_bf16 v[18:33], v[138:141], v[130:133], v[18:33]
	s_waitcnt lgkmcnt(0)
	v_mfma_f32_32x32x16_bf16 v[34:49], v[126:129], v[114:117], v[34:49]
	v_bitop3_b32 v114, v169, v167, 8 bitop3:0x36
	v_lshl_add_u32 v114, v114, 4, v165
	ds_read_b128 v[114:117], v114 offset:55296
	v_mfma_f32_32x32x16_bf16 v[2:17], v[138:141], v[134:137], v[2:17]
	v_mfma_f32_32x32x16_bf16 v[18:33], v[126:129], v[118:121], v[18:33]
	v_mfma_f32_32x32x16_bf16 v[2:17], v[126:129], v[122:125], v[2:17]
	v_lshlrev_b32_e32 v128, 7, v164
	v_or_b32_e32 v126, v128, v168
	v_ashrrev_i32_e32 v127, 31, v126
	v_lshlrev_b64 v[130:131], 2, v[126:127]
	v_lshl_or_b32 v122, v169, 2, v166
	v_or_b32_e32 v124, s3, v168
	v_mov_b32_e32 v125, s5
	s_waitcnt lgkmcnt(0)
	v_mfma_f32_32x32x16_bf16 v[18:33], v[114:117], v[106:109], v[18:33]
	v_bitop3_b32 v106, v169, v167, 10 bitop3:0x36
	v_lshl_add_u32 v106, v106, 4, v165
	ds_read_b128 v[106:109], v106 offset:55296
	v_lshl_add_u64 v[132:133], s[6:7], 0, v[130:131]
	v_lshl_add_u64 v[130:131], s[92:93], 0, v[130:131]
	v_ashrrev_i32_e32 v123, 31, v122
	v_lshlrev_b64 v[122:123], 1, v[122:123]
	v_mfma_f32_32x32x16_bf16 v[2:17], v[114:117], v[110:113], v[2:17]
	s_add_i32 s3, s3, s18
	s_cmpk_gt_i32 s4, 0x7f
	s_waitcnt lgkmcnt(0)
	v_mfma_f32_32x32x16_bf16 v[18:33], v[106:109], v[98:101], v[18:33]
	v_bitop3_b32 v98, v169, v167, 12 bitop3:0x36
	v_lshl_add_u32 v98, v98, 4, v165
	ds_read_b128 v[98:101], v98 offset:55296
	v_mfma_f32_32x32x16_bf16 v[2:17], v[106:109], v[102:105], v[2:17]
	s_waitcnt lgkmcnt(0)
	v_mfma_f32_32x32x16_bf16 v[2:17], v[98:101], v[94:97], v[2:17]
	v_bitop3_b32 v94, v169, v167, 14 bitop3:0x36
	v_lshl_add_u32 v94, v94, 4, v165
	ds_read_b128 v[94:97], v94 offset:55296
	v_ashrrev_i32_e32 v167, 31, v166
	s_waitcnt lgkmcnt(0)
	v_mfma_f32_32x32x16_bf16 v[2:17], v[94:97], v[90:93], v[2:17]
	v_lshlrev_b64 v[90:91], 2, v[166:167]
	v_lshl_add_u64 v[92:93], s[10:11], 0, v[90:91]
	v_lshl_add_u64 v[90:91], s[40:41], 0, v[90:91]
	v_lshl_add_u64 v[92:93], v[92:93], 0, v[154:155]
	v_lshl_add_u64 v[94:95], v[90:91], 0, v[154:155]
	global_load_dwordx4 v[114:117], v[92:93], off
	global_load_dwordx4 v[118:121], v[94:95], off
	global_load_dwordx4 v[106:109], v[92:93], off offset:32
	global_load_dwordx4 v[110:113], v[94:95], off offset:32
	global_load_dwordx4 v[98:101], v[92:93], off offset:64
	global_load_dwordx4 v[102:105], v[94:95], off offset:64
	s_nop 0
	global_load_dwordx4 v[90:93], v[92:93], off offset:96
	s_nop 0
	global_load_dwordx4 v[94:97], v[94:95], off offset:96
	s_nop 0
	global_load_dword v142, v[132:133], off
	global_load_dword v143, v[132:133], off offset:128
	global_load_dword v144, v[132:133], off offset:256
	global_load_dword v145, v[132:133], off offset:384
	global_load_dword v146, v[130:131], off
	global_load_dword v147, v[130:131], off offset:128
	global_load_dword v148, v[130:131], off offset:256
	global_load_dword v149, v[130:131], off offset:384
	v_lshlrev_b64 v[134:135], 11, v[124:125]
	v_lshl_add_u64 v[134:135], s[62:63], 0, v[134:135]
	v_lshl_add_u64 v[134:135], v[134:135], 0, v[122:123]
	v_add_co_u32_e32 v136, vcc, 0x10000, v134
	s_nop 1
	v_addc_co_u32_e32 v137, vcc, 0, v135, vcc
	v_add_co_u32_e32 v138, vcc, 0x20000, v134
	s_nop 1
	v_addc_co_u32_e32 v139, vcc, 0, v135, vcc
	v_add_co_u32_e32 v140, vcc, 0x30000, v134
	s_nop 1
	v_addc_co_u32_e32 v141, vcc, 0, v135, vcc
	v_and_b32_e32 v150, 31, v0
	v_lshlrev_b32_e32 v170, 6, v150
	v_bfe_u32 v151, v0, 5, 1
	v_lshl_add_u32 v170, v151, 3, v170
	v_lshrrev_b32_e32 v168, 6, v0
	v_lshl_add_u32 v170, v168, 13, v170
	v_add_u32_e32 v170, 0xd820, v170
	v_bfe_u32 v150, v0, 1, 2
	v_xor_b32_e32 v151, 0, v150
	v_lshl_add_u32 v152, v151, 4, v170
	v_xor_b32_e32 v151, 1, v150
	v_lshl_add_u32 v153, v151, 4, v170
	v_xor_b32_e32 v151, 2, v150
	v_lshl_add_u32 v164, v151, 4, v170
	v_xor_b32_e32 v151, 3, v150
	v_lshl_add_u32 v165, v151, 4, v170
	v_bfe_u32 v169, v0, 2, 4
	v_lshlrev_b32_e32 v166, 6, v169
	v_and_b32_e32 v151, 3, v0
	v_bfe_u32 v150, v0, 3, 2
	v_xor_b32_e32 v150, v151, v150
	v_lshl_add_u32 v166, v150, 4, v166
	v_lshl_add_u32 v166, v168, 13, v166
	v_add_u32_e32 v166, 0xd820, v166
	v_and_b32_e32 v167, -32, v124
	v_add_u32_e32 v167, v167, v169
	v_lshlrev_b32_e32 v167, 11, v167
	v_lshl_add_u32 v167, v168, 6, v167
	v_lshl_add_u32 v167, v151, 4, v167
	s_waitcnt vmcnt(0)
	s_nop 1
	v_permlane32_swap_b32 v216, v218
	v_permlane32_swap_b32 v217, v219
	v_permlane32_swap_b32 v220, v222
	v_permlane32_swap_b32 v221, v223
	v_permlane32_swap_b32 v224, v226
	v_permlane32_swap_b32 v225, v227
	v_permlane32_swap_b32 v228, v230
	v_permlane32_swap_b32 v229, v231
	v_permlane32_swap_b32 v232, v234
	v_permlane32_swap_b32 v233, v235
	v_permlane32_swap_b32 v236, v238
	v_permlane32_swap_b32 v237, v239
	v_permlane32_swap_b32 v252, v254
	v_permlane32_swap_b32 v253, v255
	v_mul_f32_e32 v150, v118, v142
	v_fmac_f32_e32 v150, v50, v114
	v_add_f32_e32 v50, v146, v150
	v_lshlrev_b32_e32 v151, 16, v216
	v_mul_f32_e32 v50, v50, v151
	v_mul_f32_e32 v150, v119, v142
	v_fmac_f32_e32 v150, v51, v115
	v_add_f32_e32 v51, v146, v150
	v_and_b32_e32 v151, 0xffff0000, v216
	v_mul_f32_e32 v51, v51, v151
	v_mul_f32_e32 v150, v120, v142
	v_fmac_f32_e32 v150, v52, v116
	v_add_f32_e32 v52, v146, v150
	v_lshlrev_b32_e32 v151, 16, v217
	v_mul_f32_e32 v52, v52, v151
	v_mul_f32_e32 v150, v121, v142
	v_fmac_f32_e32 v150, v53, v117
	v_add_f32_e32 v53, v146, v150
	v_and_b32_e32 v151, 0xffff0000, v217
	v_mul_f32_e32 v53, v53, v151
	v_cvt_pk_bf16_f32 v50, v50, v51
	v_cvt_pk_bf16_f32 v51, v52, v53
	ds_write_b64 v152, v[50:51] offset:0
	v_mul_f32_e32 v150, v110, v142
	v_fmac_f32_e32 v150, v54, v106
	v_add_f32_e32 v54, v146, v150
	v_lshlrev_b32_e32 v151, 16, v218
	v_mul_f32_e32 v54, v54, v151
	v_mul_f32_e32 v150, v111, v142
	v_fmac_f32_e32 v150, v55, v107
	v_add_f32_e32 v55, v146, v150
	v_and_b32_e32 v151, 0xffff0000, v218
	v_mul_f32_e32 v55, v55, v151
	v_mul_f32_e32 v150, v112, v142
	v_fmac_f32_e32 v150, v56, v108
	v_add_f32_e32 v56, v146, v150
	v_lshlrev_b32_e32 v151, 16, v219
	v_mul_f32_e32 v56, v56, v151
	v_mul_f32_e32 v150, v113, v142
	v_fmac_f32_e32 v150, v57, v109
	v_add_f32_e32 v57, v146, v150
	v_and_b32_e32 v151, 0xffff0000, v219
	v_mul_f32_e32 v57, v57, v151
	v_cvt_pk_bf16_f32 v54, v54, v55
	v_cvt_pk_bf16_f32 v55, v56, v57
	ds_write_b64 v153, v[54:55] offset:0
	v_mul_f32_e32 v150, v102, v142
	v_fmac_f32_e32 v150, v58, v98
	v_add_f32_e32 v58, v146, v150
	v_lshlrev_b32_e32 v151, 16, v220
	v_mul_f32_e32 v58, v58, v151
	v_mul_f32_e32 v150, v103, v142
	v_fmac_f32_e32 v150, v59, v99
	v_add_f32_e32 v59, v146, v150
	v_and_b32_e32 v151, 0xffff0000, v220
	v_mul_f32_e32 v59, v59, v151
	v_mul_f32_e32 v150, v104, v142
	v_fmac_f32_e32 v150, v60, v100
	v_add_f32_e32 v60, v146, v150
	v_lshlrev_b32_e32 v151, 16, v221
	v_mul_f32_e32 v60, v60, v151
	v_mul_f32_e32 v150, v105, v142
	v_fmac_f32_e32 v150, v61, v101
	v_add_f32_e32 v61, v146, v150
	v_and_b32_e32 v151, 0xffff0000, v221
	v_mul_f32_e32 v61, v61, v151
	v_cvt_pk_bf16_f32 v58, v58, v59
	v_cvt_pk_bf16_f32 v59, v60, v61
	ds_write_b64 v164, v[58:59] offset:0
	v_mul_f32_e32 v150, v94, v142
	v_fmac_f32_e32 v150, v62, v90
	v_add_f32_e32 v62, v146, v150
	v_lshlrev_b32_e32 v151, 16, v222
	v_mul_f32_e32 v62, v62, v151
	v_mul_f32_e32 v150, v95, v142
	v_fmac_f32_e32 v150, v63, v91
	v_add_f32_e32 v63, v146, v150
	v_and_b32_e32 v151, 0xffff0000, v222
	v_mul_f32_e32 v63, v63, v151
	v_mul_f32_e32 v150, v96, v142
	v_fmac_f32_e32 v150, v64, v92
	v_add_f32_e32 v64, v146, v150
	v_lshlrev_b32_e32 v151, 16, v223
	v_mul_f32_e32 v64, v64, v151
	v_mul_f32_e32 v150, v97, v142
	v_fmac_f32_e32 v150, v65, v93
	v_add_f32_e32 v65, v146, v150
	v_and_b32_e32 v151, 0xffff0000, v223
	v_mul_f32_e32 v65, v65, v151
	v_cvt_pk_bf16_f32 v62, v62, v63
	v_cvt_pk_bf16_f32 v63, v64, v65
	ds_write_b64 v165, v[62:63] offset:0
	v_mul_f32_e32 v150, v118, v143
	v_fmac_f32_e32 v150, v34, v114
	v_add_f32_e32 v34, v147, v150
	v_lshlrev_b32_e32 v151, 16, v224
	v_mul_f32_e32 v34, v34, v151
	v_mul_f32_e32 v150, v119, v143
	v_fmac_f32_e32 v150, v35, v115
	v_add_f32_e32 v35, v147, v150
	v_and_b32_e32 v151, 0xffff0000, v224
	v_mul_f32_e32 v35, v35, v151
	v_mul_f32_e32 v150, v120, v143
	v_fmac_f32_e32 v150, v36, v116
	v_add_f32_e32 v36, v147, v150
	v_lshlrev_b32_e32 v151, 16, v225
	v_mul_f32_e32 v36, v36, v151
	v_mul_f32_e32 v150, v121, v143
	v_fmac_f32_e32 v150, v37, v117
	v_add_f32_e32 v37, v147, v150
	v_and_b32_e32 v151, 0xffff0000, v225
	v_mul_f32_e32 v37, v37, v151
	v_cvt_pk_bf16_f32 v34, v34, v35
	v_cvt_pk_bf16_f32 v35, v36, v37
	ds_write_b64 v152, v[34:35] offset:2048
	v_mul_f32_e32 v150, v110, v143
	v_fmac_f32_e32 v150, v38, v106
	v_add_f32_e32 v38, v147, v150
	v_lshlrev_b32_e32 v151, 16, v226
	v_mul_f32_e32 v38, v38, v151
	v_mul_f32_e32 v150, v111, v143
	v_fmac_f32_e32 v150, v39, v107
	v_add_f32_e32 v39, v147, v150
	v_and_b32_e32 v151, 0xffff0000, v226
	v_mul_f32_e32 v39, v39, v151
	v_mul_f32_e32 v150, v112, v143
	v_fmac_f32_e32 v150, v40, v108
	v_add_f32_e32 v40, v147, v150
	v_lshlrev_b32_e32 v151, 16, v227
	v_mul_f32_e32 v40, v40, v151
	v_mul_f32_e32 v150, v113, v143
	v_fmac_f32_e32 v150, v41, v109
	v_add_f32_e32 v41, v147, v150
	v_and_b32_e32 v151, 0xffff0000, v227
	v_mul_f32_e32 v41, v41, v151
	v_cvt_pk_bf16_f32 v38, v38, v39
	v_cvt_pk_bf16_f32 v39, v40, v41
	ds_write_b64 v153, v[38:39] offset:2048
	v_mul_f32_e32 v150, v102, v143
	v_fmac_f32_e32 v150, v42, v98
	v_add_f32_e32 v42, v147, v150
	v_lshlrev_b32_e32 v151, 16, v228
	v_mul_f32_e32 v42, v42, v151
	v_mul_f32_e32 v150, v103, v143
	v_fmac_f32_e32 v150, v43, v99
	v_add_f32_e32 v43, v147, v150
	v_and_b32_e32 v151, 0xffff0000, v228
	v_mul_f32_e32 v43, v43, v151
	v_mul_f32_e32 v150, v104, v143
	v_fmac_f32_e32 v150, v44, v100
	v_add_f32_e32 v44, v147, v150
	v_lshlrev_b32_e32 v151, 16, v229
	v_mul_f32_e32 v44, v44, v151
	v_mul_f32_e32 v150, v105, v143
	v_fmac_f32_e32 v150, v45, v101
	v_add_f32_e32 v45, v147, v150
	v_and_b32_e32 v151, 0xffff0000, v229
	v_mul_f32_e32 v45, v45, v151
	v_cvt_pk_bf16_f32 v42, v42, v43
	v_cvt_pk_bf16_f32 v43, v44, v45
	ds_write_b64 v164, v[42:43] offset:2048
	v_mul_f32_e32 v150, v94, v143
	v_fmac_f32_e32 v150, v46, v90
	v_add_f32_e32 v46, v147, v150
	v_lshlrev_b32_e32 v151, 16, v230
	v_mul_f32_e32 v46, v46, v151
	v_mul_f32_e32 v150, v95, v143
	v_fmac_f32_e32 v150, v47, v91
	v_add_f32_e32 v47, v147, v150
	v_and_b32_e32 v151, 0xffff0000, v230
	v_mul_f32_e32 v47, v47, v151
	v_mul_f32_e32 v150, v96, v143
	v_fmac_f32_e32 v150, v48, v92
	v_add_f32_e32 v48, v147, v150
	v_lshlrev_b32_e32 v151, 16, v231
	v_mul_f32_e32 v48, v48, v151
	v_mul_f32_e32 v150, v97, v143
	v_fmac_f32_e32 v150, v49, v93
	v_add_f32_e32 v49, v147, v150
	v_and_b32_e32 v151, 0xffff0000, v231
	v_mul_f32_e32 v49, v49, v151
	v_cvt_pk_bf16_f32 v46, v46, v47
	v_cvt_pk_bf16_f32 v47, v48, v49
	ds_write_b64 v165, v[46:47] offset:2048
	v_mul_f32_e32 v150, v118, v144
	v_fmac_f32_e32 v150, v18, v114
	v_add_f32_e32 v18, v148, v150
	v_lshlrev_b32_e32 v151, 16, v232
	v_mul_f32_e32 v18, v18, v151
	v_mul_f32_e32 v150, v119, v144
	v_fmac_f32_e32 v150, v19, v115
	v_add_f32_e32 v19, v148, v150
	v_and_b32_e32 v151, 0xffff0000, v232
	v_mul_f32_e32 v19, v19, v151
	v_mul_f32_e32 v150, v120, v144
	v_fmac_f32_e32 v150, v20, v116
	v_add_f32_e32 v20, v148, v150
	v_lshlrev_b32_e32 v151, 16, v233
	v_mul_f32_e32 v20, v20, v151
	v_mul_f32_e32 v150, v121, v144
	v_fmac_f32_e32 v150, v21, v117
	v_add_f32_e32 v21, v148, v150
	v_and_b32_e32 v151, 0xffff0000, v233
	v_mul_f32_e32 v21, v21, v151
	v_cvt_pk_bf16_f32 v18, v18, v19
	v_cvt_pk_bf16_f32 v19, v20, v21
	ds_write_b64 v152, v[18:19] offset:4096
	v_mul_f32_e32 v150, v110, v144
	v_fmac_f32_e32 v150, v22, v106
	v_add_f32_e32 v22, v148, v150
	v_lshlrev_b32_e32 v151, 16, v234
	v_mul_f32_e32 v22, v22, v151
	v_mul_f32_e32 v150, v111, v144
	v_fmac_f32_e32 v150, v23, v107
	v_add_f32_e32 v23, v148, v150
	v_and_b32_e32 v151, 0xffff0000, v234
	v_mul_f32_e32 v23, v23, v151
	v_mul_f32_e32 v150, v112, v144
	v_fmac_f32_e32 v150, v24, v108
	v_add_f32_e32 v24, v148, v150
	v_lshlrev_b32_e32 v151, 16, v235
	v_mul_f32_e32 v24, v24, v151
	v_mul_f32_e32 v150, v113, v144
	v_fmac_f32_e32 v150, v25, v109
	v_add_f32_e32 v25, v148, v150
	v_and_b32_e32 v151, 0xffff0000, v235
	v_mul_f32_e32 v25, v25, v151
	v_cvt_pk_bf16_f32 v22, v22, v23
	v_cvt_pk_bf16_f32 v23, v24, v25
	ds_write_b64 v153, v[22:23] offset:4096
	v_mul_f32_e32 v150, v102, v144
	v_fmac_f32_e32 v150, v26, v98
	v_add_f32_e32 v26, v148, v150
	v_lshlrev_b32_e32 v151, 16, v236
	v_mul_f32_e32 v26, v26, v151
	v_mul_f32_e32 v150, v103, v144
	v_fmac_f32_e32 v150, v27, v99
	v_add_f32_e32 v27, v148, v150
	v_and_b32_e32 v151, 0xffff0000, v236
	v_mul_f32_e32 v27, v27, v151
	v_mul_f32_e32 v150, v104, v144
	v_fmac_f32_e32 v150, v28, v100
	v_add_f32_e32 v28, v148, v150
	v_lshlrev_b32_e32 v151, 16, v237
	v_mul_f32_e32 v28, v28, v151
	v_mul_f32_e32 v150, v105, v144
	v_fmac_f32_e32 v150, v29, v101
	v_add_f32_e32 v29, v148, v150
	v_and_b32_e32 v151, 0xffff0000, v237
	v_mul_f32_e32 v29, v29, v151
	v_cvt_pk_bf16_f32 v26, v26, v27
	v_cvt_pk_bf16_f32 v27, v28, v29
	ds_write_b64 v164, v[26:27] offset:4096
	v_mul_f32_e32 v150, v94, v144
	v_fmac_f32_e32 v150, v30, v90
	v_add_f32_e32 v30, v148, v150
	v_lshlrev_b32_e32 v151, 16, v238
	v_mul_f32_e32 v30, v30, v151
	v_mul_f32_e32 v150, v95, v144
	v_fmac_f32_e32 v150, v31, v91
	v_add_f32_e32 v31, v148, v150
	v_and_b32_e32 v151, 0xffff0000, v238
	v_mul_f32_e32 v31, v31, v151
	v_mul_f32_e32 v150, v96, v144
	v_fmac_f32_e32 v150, v32, v92
	v_add_f32_e32 v32, v148, v150
	v_lshlrev_b32_e32 v151, 16, v239
	v_mul_f32_e32 v32, v32, v151
	v_mul_f32_e32 v150, v97, v144
	v_fmac_f32_e32 v150, v33, v93
	v_add_f32_e32 v33, v148, v150
	v_and_b32_e32 v151, 0xffff0000, v239
	v_mul_f32_e32 v33, v33, v151
	v_cvt_pk_bf16_f32 v30, v30, v31
	v_cvt_pk_bf16_f32 v31, v32, v33
	ds_write_b64 v165, v[30:31] offset:4096
	v_mul_f32_e32 v150, v118, v145
	v_fmac_f32_e32 v150, v2, v114
	v_add_f32_e32 v2, v149, v150
	v_lshlrev_b32_e32 v151, 16, v252
	v_mul_f32_e32 v2, v2, v151
	v_mul_f32_e32 v150, v119, v145
	v_fmac_f32_e32 v150, v3, v115
	v_add_f32_e32 v3, v149, v150
	v_and_b32_e32 v151, 0xffff0000, v252
	v_mul_f32_e32 v3, v3, v151
	v_mul_f32_e32 v150, v120, v145
	v_fmac_f32_e32 v150, v4, v116
	v_add_f32_e32 v4, v149, v150
	v_lshlrev_b32_e32 v151, 16, v253
	v_mul_f32_e32 v4, v4, v151
	v_mul_f32_e32 v150, v121, v145
	v_fmac_f32_e32 v150, v5, v117
	v_add_f32_e32 v5, v149, v150
	v_and_b32_e32 v151, 0xffff0000, v253
	v_mul_f32_e32 v5, v5, v151
	v_cvt_pk_bf16_f32 v2, v2, v3
	v_cvt_pk_bf16_f32 v3, v4, v5
	ds_write_b64 v152, v[2:3] offset:6144
	v_mul_f32_e32 v150, v110, v145
	v_fmac_f32_e32 v150, v6, v106
	v_add_f32_e32 v6, v149, v150
	v_lshlrev_b32_e32 v151, 16, v254
	v_mul_f32_e32 v6, v6, v151
	v_mul_f32_e32 v150, v111, v145
	v_fmac_f32_e32 v150, v7, v107
	v_add_f32_e32 v7, v149, v150
	v_and_b32_e32 v151, 0xffff0000, v254
	v_mul_f32_e32 v7, v7, v151
	v_mul_f32_e32 v150, v112, v145
	v_fmac_f32_e32 v150, v8, v108
	v_add_f32_e32 v8, v149, v150
	v_lshlrev_b32_e32 v151, 16, v255
	v_mul_f32_e32 v8, v8, v151
	v_mul_f32_e32 v150, v113, v145
	v_fmac_f32_e32 v150, v9, v109
	v_add_f32_e32 v9, v149, v150
	v_and_b32_e32 v151, 0xffff0000, v255
	v_mul_f32_e32 v9, v9, v151
	v_cvt_pk_bf16_f32 v6, v6, v7
	v_cvt_pk_bf16_f32 v7, v8, v9
	ds_write_b64 v153, v[6:7] offset:6144
	v_mul_f32_e32 v150, v102, v145
	v_fmac_f32_e32 v150, v10, v98
	v_add_f32_e32 v10, v149, v150
	v_lshlrev_b32_e32 v151, 16, v240
	v_mul_f32_e32 v10, v10, v151
	v_mul_f32_e32 v150, v103, v145
	v_fmac_f32_e32 v150, v11, v99
	v_add_f32_e32 v11, v149, v150
	v_and_b32_e32 v151, 0xffff0000, v240
	v_mul_f32_e32 v11, v11, v151
	v_mul_f32_e32 v150, v104, v145
	v_fmac_f32_e32 v150, v12, v100
	v_add_f32_e32 v12, v149, v150
	v_lshlrev_b32_e32 v151, 16, v241
	v_mul_f32_e32 v12, v12, v151
	v_mul_f32_e32 v150, v105, v145
	v_fmac_f32_e32 v150, v13, v101
	v_add_f32_e32 v13, v149, v150
	v_and_b32_e32 v151, 0xffff0000, v241
	v_mul_f32_e32 v13, v13, v151
	v_cvt_pk_bf16_f32 v10, v10, v11
	v_cvt_pk_bf16_f32 v11, v12, v13
	ds_write_b64 v164, v[10:11] offset:6144
	v_mul_f32_e32 v150, v94, v145
	v_fmac_f32_e32 v150, v14, v90
	v_add_f32_e32 v14, v149, v150
	v_lshlrev_b32_e32 v151, 16, v246
	v_mul_f32_e32 v14, v14, v151
	v_mul_f32_e32 v150, v95, v145
	v_fmac_f32_e32 v150, v15, v91
	v_add_f32_e32 v15, v149, v150
	v_and_b32_e32 v151, 0xffff0000, v246
	v_mul_f32_e32 v15, v15, v151
	v_mul_f32_e32 v150, v96, v145
	v_fmac_f32_e32 v150, v16, v92
	v_add_f32_e32 v16, v149, v150
	v_lshlrev_b32_e32 v151, 16, v247
	v_mul_f32_e32 v16, v16, v151
	v_mul_f32_e32 v150, v97, v145
	v_fmac_f32_e32 v150, v17, v93
	v_add_f32_e32 v17, v149, v150
	v_and_b32_e32 v151, 0xffff0000, v247
	v_mul_f32_e32 v17, v17, v151
	v_cvt_pk_bf16_f32 v14, v14, v15
	v_cvt_pk_bf16_f32 v15, v16, v17
	ds_write_b64 v165, v[14:15] offset:6144
	s_waitcnt lgkmcnt(0)
	ds_read_b128 v[2:5], v166 offset:0
	ds_read_b128 v[6:9], v166 offset:1024
	ds_read_b128 v[10:13], v166 offset:2048
	ds_read_b128 v[14:17], v166 offset:3072
	ds_read_b128 v[18:21], v166 offset:4096
	ds_read_b128 v[22:25], v166 offset:5120
	ds_read_b128 v[26:29], v166 offset:6144
	ds_read_b128 v[30:33], v166 offset:7168
	s_waitcnt lgkmcnt(7)
	global_store_dwordx4 v167, v[2:5], s[62:63] offset:1536
	v_add_u32_e32 v151, 0x8000, v167
	s_waitcnt lgkmcnt(6)
	global_store_dwordx4 v151, v[6:9], s[62:63] offset:1536
	v_add_u32_e32 v150, 0x10000, v167
	s_waitcnt lgkmcnt(5)
	global_store_dwordx4 v150, v[10:13], s[62:63] offset:1536
	v_add_u32_e32 v151, 0x18000, v167
	s_waitcnt lgkmcnt(4)
	global_store_dwordx4 v151, v[14:17], s[62:63] offset:1536
	v_add_u32_e32 v150, 0x20000, v167
	s_waitcnt lgkmcnt(3)
	global_store_dwordx4 v150, v[18:21], s[62:63] offset:1536
	v_add_u32_e32 v151, 0x28000, v167
	s_waitcnt lgkmcnt(2)
	global_store_dwordx4 v151, v[22:25], s[62:63] offset:1536
	v_add_u32_e32 v150, 0x30000, v167
	s_waitcnt lgkmcnt(1)
	global_store_dwordx4 v150, v[26:29], s[62:63] offset:1536
	v_add_u32_e32 v151, 0x38000, v167
	s_waitcnt lgkmcnt(0)
	global_store_dwordx4 v151, v[30:33], s[62:63] offset:1536
	s_barrier
	s_cbranch_scc0 .LBB0_779

.LBB0_849:
	v_mov_b32_e32 v43, v0
	s_ashr_i32 s5, s3, 31
	v_ashrrev_i32_e32 v44, 7, v43
	s_waitcnt vmcnt(7)
	v_add_u32_e32 v130, s2, v44
	v_ashrrev_i32_e32 v131, 31, v130
	v_and_b32_e32 v134, 31, v43
	s_waitcnt vmcnt(0)
	v_lshlrev_b64 v[2:3], 15, v[130:131]
	v_bfe_u32 v135, v43, 5, 1
	v_lshl_add_u64 v[2:3], s[56:57], 0, v[2:3]
	v_and_b32_e32 v18, 63, v43
	v_lshlrev_b32_e32 v18, 4, v18
	v_lshlrev_b32_e32 v154, 4, v135
	v_add_u32_e32 v18, 0x1000, v18
	v_add_co_u32_e32 v18, vcc, v2, v18
	s_nop 1
	v_addc_co_u32_e32 v19, vcc, 0, v3, vcc
	v_add_co_u32_e32 v20, vcc, s14, v18
	v_ashrrev_i32_e32 v45, 2, v43
	s_nop 0
	v_addc_co_u32_e32 v21, vcc, 0, v19, vcc
	v_add_co_u32_e32 v22, vcc, s17, v18
	global_load_dwordx4 v[2:5], v[18:19], off offset:-4096
	global_load_dwordx4 v[6:9], v[20:21], off offset:-4096
	v_addc_co_u32_e32 v23, vcc, 0, v19, vcc
	v_add_co_u32_e32 v24, vcc, s30, v18
	global_load_dwordx4 v[10:13], v[22:23], off offset:-4096
	s_nop 0
	v_addc_co_u32_e32 v25, vcc, 0, v19, vcc
	global_load_dwordx4 v[14:17], v[24:25], off offset:-4096
	global_load_dwordx4 v[114:117], v[18:19], off offset:-3072
	global_load_dwordx4 v[118:121], v[20:21], off offset:-3072
	global_load_dwordx4 v[122:125], v[22:23], off offset:-3072
	global_load_dwordx4 v[126:129], v[24:25], off offset:-3072
	global_load_dwordx4 v[102:105], v[20:21], off offset:-2048
	global_load_dwordx4 v[106:109], v[22:23], off offset:-2048
	global_load_dwordx4 v[110:113], v[24:25], off offset:-2048
	global_load_dwordx4 v[90:93], v[20:21], off offset:-1024
	global_load_dwordx4 v[94:97], v[22:23], off offset:-1024
	global_load_dwordx4 v[98:101], v[24:25], off offset:-1024
	global_load_dwordx4 v[82:85], v[22:23], off
	global_load_dwordx4 v[86:89], v[24:25], off
	global_load_dwordx4 v[74:77], v[22:23], off offset:1024
	global_load_dwordx4 v[78:81], v[24:25], off offset:1024
	global_load_dwordx4 v[70:73], v[24:25], off offset:2048
	global_load_dwordx4 v[66:69], v[24:25], off offset:3072
	v_add_u32_e32 v18, s3, v45
	v_ashrrev_i32_e32 v19, 31, v18
	v_lshlrev_b32_e32 v20, 6, v43
	v_lshlrev_b64 v[18:19], 12, v[18:19]
	v_and_b32_e32 v46, 0xc0, v20
	v_lshl_add_u64 v[18:19], s[60:61], 0, v[18:19]
	v_lshlrev_b32_e32 v20, 1, v46
	v_mov_b32_e32 v21, v155
	v_lshl_add_u64 v[34:35], v[18:19], 0, v[20:21]
	global_load_dwordx4 v[18:21], v[34:35], off offset:3632
	global_load_dwordx4 v[22:25], v[34:35], off offset:3616
	global_load_dwordx4 v[26:29], v[34:35], off offset:3600
	global_load_dwordx4 v[30:33], v[34:35], off offset:3584
	global_load_dwordx4 v[36:39], v[34:35], off offset:3680
	global_load_dwordx4 v[176:179], v[34:35], off offset:3664
	global_load_dwordx4 v[48:51], v[34:35], off offset:3648
	global_load_dwordx4 v[182:185], v[34:35], off offset:3696
	v_lshrrev_b32_e32 v42, 5, v43
	s_add_i32 s4, s4, s46
	s_waitcnt vmcnt(7)
	v_lshlrev_b32_e32 v144, 16, v18
	s_waitcnt vmcnt(6)
	v_lshlrev_b32_e32 v150, 16, v22
	s_waitcnt vmcnt(5)
	v_lshlrev_b32_e32 v168, 16, v26
	s_waitcnt vmcnt(4)
	v_lshlrev_b32_e32 v174, 16, v30
	v_and_b32_e32 v173, 0xffff0000, v30
	v_add_f32_e32 v30, 0, v174
	v_lshlrev_b32_e32 v172, 16, v31
	v_add_f32_e32 v30, v30, v173
	v_and_b32_e32 v171, 0xffff0000, v31
	v_mul_f32_e32 v31, v173, v173
	v_add_f32_e32 v30, v30, v172
	v_lshlrev_b32_e32 v170, 16, v32
	v_fmac_f32_e32 v31, v174, v174
	v_add_f32_e32 v30, v30, v171
	v_and_b32_e32 v169, 0xffff0000, v32
	v_fmac_f32_e32 v31, v172, v172
	v_add_f32_e32 v30, v30, v170
	v_lshlrev_b32_e32 v167, 16, v33
	v_fmac_f32_e32 v31, v171, v171
	v_add_f32_e32 v30, v30, v169
	v_and_b32_e32 v165, 0xffff0000, v33
	v_fmac_f32_e32 v31, v170, v170
	v_add_f32_e32 v30, v30, v167
	v_fmac_f32_e32 v31, v169, v169
	v_add_f32_e32 v30, v30, v165
	v_fmac_f32_e32 v31, v167, v167
	v_and_b32_e32 v166, 0xffff0000, v26
	v_add_f32_e32 v26, v30, v168
	v_fmac_f32_e32 v31, v165, v165
	v_lshlrev_b32_e32 v164, 16, v27
	v_add_f32_e32 v26, v26, v166
	v_and_b32_e32 v153, 0xffff0000, v27
	v_fmac_f32_e32 v31, v168, v168
	v_add_f32_e32 v26, v26, v164
	v_lshlrev_b32_e32 v152, 16, v28
	v_fmac_f32_e32 v31, v166, v166
	v_add_f32_e32 v26, v26, v153
	v_and_b32_e32 v151, 0xffff0000, v28
	v_fmac_f32_e32 v31, v164, v164
	v_add_f32_e32 v26, v26, v152
	v_lshlrev_b32_e32 v148, 16, v29
	v_fmac_f32_e32 v31, v153, v153
	v_add_f32_e32 v26, v26, v151
	v_and_b32_e32 v146, 0xffff0000, v29
	v_fmac_f32_e32 v31, v152, v152
	v_add_f32_e32 v26, v26, v148
	v_fmac_f32_e32 v31, v151, v151
	v_add_f32_e32 v26, v26, v146
	v_fmac_f32_e32 v31, v148, v148
	v_and_b32_e32 v149, 0xffff0000, v22
	v_add_f32_e32 v22, v26, v150
	v_fmac_f32_e32 v31, v146, v146
	v_lshlrev_b32_e32 v147, 16, v23
	v_add_f32_e32 v22, v22, v149
	v_and_b32_e32 v145, 0xffff0000, v23
	v_fmac_f32_e32 v31, v150, v150
	v_add_f32_e32 v22, v22, v147
	v_lshlrev_b32_e32 v143, 16, v24
	v_fmac_f32_e32 v31, v149, v149
	v_add_f32_e32 v22, v22, v145
	v_and_b32_e32 v141, 0xffff0000, v24
	v_fmac_f32_e32 v31, v147, v147
	v_add_f32_e32 v22, v22, v143
	v_lshlrev_b32_e32 v139, 16, v25
	v_fmac_f32_e32 v31, v145, v145
	v_add_f32_e32 v22, v22, v141
	v_and_b32_e32 v137, 0xffff0000, v25
	v_fmac_f32_e32 v31, v143, v143
	v_add_f32_e32 v22, v22, v139
	v_fmac_f32_e32 v31, v141, v141
	v_add_f32_e32 v22, v22, v137
	v_fmac_f32_e32 v31, v139, v139
	v_and_b32_e32 v142, 0xffff0000, v18
	v_add_f32_e32 v18, v22, v144
	v_fmac_f32_e32 v31, v137, v137
	v_lshlrev_b32_e32 v140, 16, v19
	v_add_f32_e32 v18, v18, v142
	v_and_b32_e32 v138, 0xffff0000, v19
	v_fmac_f32_e32 v31, v144, v144
	v_add_f32_e32 v18, v18, v140
	v_lshlrev_b32_e32 v133, 16, v20
	v_fmac_f32_e32 v31, v142, v142
	v_add_f32_e32 v18, v18, v138
	v_and_b32_e32 v131, 0xffff0000, v20
	v_fmac_f32_e32 v31, v140, v140
	v_add_f32_e32 v18, v18, v133
	v_lshlrev_b32_e32 v64, 16, v21
	v_fmac_f32_e32 v31, v138, v138
	v_add_f32_e32 v18, v18, v131
	v_and_b32_e32 v62, 0xffff0000, v21
	v_fmac_f32_e32 v31, v133, v133
	v_add_f32_e32 v18, v18, v64
	v_fmac_f32_e32 v31, v131, v131
	v_add_f32_e32 v18, v18, v62
	s_waitcnt vmcnt(1)
	v_lshlrev_b32_e32 v136, 16, v48
	v_fmac_f32_e32 v31, v64, v64
	v_and_b32_e32 v132, 0xffff0000, v48
	v_add_f32_e32 v18, v18, v136
	v_fmac_f32_e32 v31, v62, v62
	v_lshlrev_b32_e32 v65, 16, v49
	v_add_f32_e32 v18, v18, v132
	v_and_b32_e32 v63, 0xffff0000, v49
	v_fmac_f32_e32 v31, v136, v136
	v_add_f32_e32 v18, v18, v65
	v_lshlrev_b32_e32 v60, 16, v50
	v_fmac_f32_e32 v31, v132, v132
	v_add_f32_e32 v18, v18, v63
	v_and_b32_e32 v59, 0xffff0000, v50
	v_fmac_f32_e32 v31, v65, v65
	v_add_f32_e32 v18, v18, v60
	v_lshlrev_b32_e32 v57, 16, v51
	v_fmac_f32_e32 v31, v63, v63
	v_add_f32_e32 v18, v18, v59
	v_and_b32_e32 v55, 0xffff0000, v51
	v_fmac_f32_e32 v31, v60, v60
	v_add_f32_e32 v18, v18, v57
	v_fmac_f32_e32 v31, v59, v59
	v_add_f32_e32 v18, v18, v55
	v_lshlrev_b32_e32 v61, 16, v176
	v_fmac_f32_e32 v31, v57, v57
	v_and_b32_e32 v58, 0xffff0000, v176
	v_add_f32_e32 v18, v18, v61
	v_fmac_f32_e32 v31, v55, v55
	v_lshlrev_b32_e32 v56, 16, v177
	v_add_f32_e32 v18, v18, v58
	v_and_b32_e32 v54, 0xffff0000, v177
	v_fmac_f32_e32 v31, v61, v61
	v_add_f32_e32 v18, v18, v56
	v_lshlrev_b32_e32 v53, 16, v178
	v_fmac_f32_e32 v31, v58, v58
	v_add_f32_e32 v18, v18, v54
	v_and_b32_e32 v51, 0xffff0000, v178
	v_fmac_f32_e32 v31, v56, v56
	v_add_f32_e32 v18, v18, v53
	v_lshlrev_b32_e32 v49, 16, v179
	v_fmac_f32_e32 v31, v54, v54
	v_add_f32_e32 v18, v18, v51
	v_and_b32_e32 v47, 0xffff0000, v179
	v_fmac_f32_e32 v31, v53, v53
	v_add_f32_e32 v18, v18, v49
	v_fmac_f32_e32 v31, v51, v51
	v_add_f32_e32 v18, v18, v47
	v_lshlrev_b32_e32 v52, 16, v36
	v_fmac_f32_e32 v31, v49, v49
	v_and_b32_e32 v50, 0xffff0000, v36
	v_add_f32_e32 v18, v18, v52
	v_fmac_f32_e32 v31, v47, v47
	v_lshlrev_b32_e32 v48, 16, v37
	v_add_f32_e32 v18, v18, v50
	v_fmac_f32_e32 v31, v52, v52
	v_add_f32_e32 v18, v18, v48
	v_and_b32_e32 v37, 0xffff0000, v37
	v_fmac_f32_e32 v31, v50, v50
	v_lshlrev_b32_e32 v34, 16, v38
	v_mov_b32_e32 v35, v37
	v_add_f32_e32 v20, v18, v37
	v_fmac_f32_e32 v31, v48, v48
	v_and_b32_e32 v24, 0xffff0000, v38
	v_pk_mul_f32 v[18:19], v[34:35], v[34:35]
	v_add_f32_e32 v20, v20, v34
	v_lshlrev_b32_e32 v25, 16, v39
	v_add_f32_e32 v19, v19, v31
	v_add_f32_e32 v20, v20, v24
	v_add_f32_e32 v21, v18, v19
	v_pk_mul_f32 v[18:19], v[24:25], v[24:25]
	v_add_f32_e32 v20, v20, v25
	v_and_b32_e32 v33, 0xffff0000, v39
	v_add_f32_e32 v18, v18, v21
	s_waitcnt vmcnt(0)
	v_lshlrev_b32_e32 v28, 16, v182
	v_mov_b32_e32 v29, v33
	v_add_f32_e32 v20, v20, v33
	v_add_f32_e32 v21, v19, v18
	v_and_b32_e32 v22, 0xffff0000, v182
	v_pk_mul_f32 v[18:19], v[28:29], v[28:29]
	v_add_f32_e32 v20, v20, v28
	v_lshlrev_b32_e32 v23, 16, v183
	v_add_f32_e32 v19, v19, v21
	v_add_f32_e32 v20, v20, v22
	v_add_f32_e32 v21, v18, v19
	v_pk_mul_f32 v[18:19], v[22:23], v[22:23]
	v_add_f32_e32 v29, v20, v23
	v_and_b32_e32 v31, 0xffff0000, v183
	v_add_f32_e32 v18, v18, v21
	v_lshlrev_b32_e32 v26, 16, v184
	v_mov_b32_e32 v27, v31
	v_add_f32_e32 v29, v29, v31
	v_and_b32_e32 v36, s0, v38
	v_add_f32_e32 v18, v19, v18
	v_and_b32_e32 v20, 0xffff0000, v184
	v_pk_mul_f32 v[38:39], v[26:27], v[26:27]
	v_add_f32_e32 v27, v29, v26
	v_lshlrev_b32_e32 v21, 16, v185
	v_add_f32_e32 v18, v39, v18
	v_add_f32_e32 v27, v27, v20
	v_and_b32_e32 v29, 64, v181
	v_add_f32_e32 v18, v38, v18
	v_pk_mul_f32 v[40:41], v[20:21], v[20:21]
	v_add_f32_e32 v39, v27, v21
	v_xor_b32_e32 v27, 1, v181
	v_add_u32_e32 v29, 64, v29
	v_and_b32_e32 v19, 0xffff0000, v185
	v_add_f32_e32 v18, v40, v18
	v_cmp_lt_i32_e32 vcc, v27, v29
	v_add_f32_e32 v18, v41, v18
	v_mul_f32_e32 v38, v19, v19
	v_cndmask_b32_e32 v27, v181, v27, vcc
	v_lshlrev_b32_e32 v27, 2, v27
	v_pk_add_f32 v[38:39], v[38:39], v[18:19]
	ds_bpermute_b32 v41, v27, v39
	ds_bpermute_b32 v40, v27, v38
	v_xor_b32_e32 v35, 2, v181
	v_cmp_lt_i32_e32 vcc, v35, v29
	v_and_b32_e32 v30, s0, v182
	v_mov_b32_e32 v32, v36
	v_cndmask_b32_e32 v29, v181, v35, vcc
	v_lshlrev_b32_e32 v29, 2, v29
	s_waitcnt lgkmcnt(0)
	v_pk_add_f32 v[38:39], v[38:39], v[40:41]
	ds_bpermute_b32 v41, v29, v39
	ds_bpermute_b32 v40, v29, v38
	s_waitcnt lgkmcnt(0)
	v_pk_add_f32 v[40:41], v[38:39], v[40:41]
	s_nop 0
	v_pk_mul_f32 v[38:39], v[40:41], s[22:23] op_sel_hi:[1,0]
	v_pk_fma_f32 v[36:37], v[40:41], s[22:23], v[36:37] op_sel_hi:[1,0,1] neg_lo:[1,0,0] neg_hi:[1,0,0]
	v_fma_f32 v18, -v39, v39, v38
	v_max_f32_e32 v18, 0, v18
	v_add_f32_e32 v18, 0x358637bd, v18
	v_cmp_gt_f32_e32 vcc, s33, v18
	v_mul_f32_e32 v27, 0x4b800000, v18
	v_sub_f32_e32 v29, v174, v39
	v_cndmask_b32_e32 v18, v18, v27, vcc
	v_rsq_f32_e32 v18, v18
	v_sub_f32_e32 v19, v19, v39
	v_mul_f32_e32 v27, 0x45800000, v18
	v_cndmask_b32_e32 v18, v18, v27, vcc
	v_mul_f32_e32 v29, v29, v18
	v_lshlrev_b32_e32 v27, 1, v45
	v_bfe_u32 v35, v29, 16, 1
	v_ashrrev_i32_e32 v45, 1, v43
	v_and_b32_e32 v27, 14, v27
	v_add3_u32 v29, v29, v35, s15
	v_lshl_add_u32 v35, v46, 8, 32
	v_and_b32_e32 v46, -16, v45
	v_add3_u32 v174, v35, v46, v27
	ds_write_b16_d16_hi v174, v29 offset:55296
	v_mul_f32_e64 v215, -v39, v18
	v_fma_f32 v29, v173, v18, v215
	v_cvt_pk_bf16_f32 v29, v29, v29
	v_bitop3_b32 v173, v45, 16, -16 bitop3:0x6c
	v_add3_u32 v175, v35, v173, v27
	ds_write_b16 v175, v29 offset:55552
	v_fma_f32 v29, v172, v18, v215
	v_cvt_pk_bf16_f32 v29, v29, v29
	v_bitop3_b32 v172, v45, 32, -16 bitop3:0x6c
	v_add3_u32 v176, v35, v172, v27
	ds_write_b16 v176, v29 offset:55808
	v_fma_f32 v29, v171, v18, v215
	v_cvt_pk_bf16_f32 v29, v29, v29
	v_bitop3_b32 v171, v45, 48, -16 bitop3:0x6c
	v_add3_u32 v177, v35, v171, v27
	ds_write_b16 v177, v29 offset:56064
	v_fma_f32 v29, v170, v18, v215
	v_cvt_pk_bf16_f32 v29, v29, v29
	v_bitop3_b32 v170, v45, 64, -16 bitop3:0x6c
	v_add3_u32 v178, v35, v170, v27
	ds_write_b16 v178, v29 offset:56320
	v_fma_f32 v29, v169, v18, v215
	v_cvt_pk_bf16_f32 v29, v29, v29
	v_bitop3_b32 v169, v45, s34, -16 bitop3:0x6c
	v_add3_u32 v179, v35, v169, v27
	ds_write_b16 v179, v29 offset:56576
	v_fma_f32 v29, v167, v18, v215
	v_cvt_pk_bf16_f32 v29, v29, v29
	v_bitop3_b32 v167, v45, s31, -16 bitop3:0x6c
	v_add3_u32 v182, v35, v167, v27
	ds_write_b16 v182, v29 offset:56832
	v_fma_f32 v29, v165, v18, v215
	v_cvt_pk_bf16_f32 v29, v29, v29
	v_bitop3_b32 v165, v45, s13, -16 bitop3:0x6c
	v_add3_u32 v183, v35, v165, v27
	ds_write_b16 v183, v29 offset:57088
	v_fma_f32 v29, v168, v18, v215
	v_cvt_pk_bf16_f32 v29, v29, v29
	v_bitop3_b32 v168, v45, s12, -16 bitop3:0x6c
	v_add3_u32 v184, v35, v168, v27
	ds_write_b16 v184, v29 offset:57344
	v_fma_f32 v29, v166, v18, v215
	v_cvt_pk_bf16_f32 v29, v29, v29
	v_bitop3_b32 v166, v45, s35, -16 bitop3:0x6c
	v_add3_u32 v185, v35, v166, v27
	ds_write_b16 v185, v29 offset:57600
	v_fma_f32 v29, v164, v18, v215
	v_cvt_pk_bf16_f32 v29, v29, v29
	v_bitop3_b32 v164, v45, s38, -16 bitop3:0x6c
	v_add3_u32 v186, v35, v164, v27
	ds_write_b16 v186, v29 offset:57856
	v_fma_f32 v29, v153, v18, v215
	v_cvt_pk_bf16_f32 v29, v29, v29
	v_bitop3_b32 v153, v45, s39, -16 bitop3:0x6c
	v_add3_u32 v187, v35, v153, v27
	ds_write_b16 v187, v29 offset:58112
	v_fma_f32 v29, v152, v18, v215
	v_cvt_pk_bf16_f32 v29, v29, v29
	v_bitop3_b32 v152, v45, s16, -16 bitop3:0x6c
	v_add3_u32 v188, v35, v152, v27
	ds_write_b16 v188, v29 offset:58368
	v_fma_f32 v29, v151, v18, v215
	v_cvt_pk_bf16_f32 v29, v29, v29
	v_bitop3_b32 v151, v45, s40, -16 bitop3:0x6c
	v_add3_u32 v189, v35, v151, v27
	ds_write_b16 v189, v29 offset:58624
	v_fma_f32 v29, v148, v18, v215
	v_cvt_pk_bf16_f32 v29, v29, v29
	v_bitop3_b32 v148, v45, s41, -16 bitop3:0x6c
	v_add3_u32 v190, v35, v148, v27
	ds_write_b16 v190, v29 offset:58880
	v_sub_f32_e32 v29, v146, v39
	v_mul_f32_e32 v29, v29, v18
	v_bfe_u32 v146, v29, 16, 1
	v_bitop3_b32 v45, v45, s42, -16 bitop3:0x6c
	v_add_u32_e32 v38, 0xd800, v35
	v_add3_u32 v29, v29, v146, s15
	v_add3_u32 v35, v35, v45, v27
	ds_write_b16_d16_hi v35, v29 offset:59136
	v_fma_f32 v29, v150, v18, v215
	v_cvt_pk_bf16_f32 v29, v29, v29
	ds_write_b16 v174, v29 offset:59392
	v_fma_f32 v29, v149, v18, v215
	v_cvt_pk_bf16_f32 v29, v29, v29
	ds_write_b16 v175, v29 offset:59648
	v_fma_f32 v29, v147, v18, v215
	v_cvt_pk_bf16_f32 v29, v29, v29
	ds_write_b16 v176, v29 offset:59904
	v_fma_f32 v29, v145, v18, v215
	v_cvt_pk_bf16_f32 v29, v29, v29
	ds_write_b16 v177, v29 offset:60160
	v_fma_f32 v29, v143, v18, v215
	v_cvt_pk_bf16_f32 v29, v29, v29
	ds_write_b16 v178, v29 offset:60416
	v_fma_f32 v29, v141, v18, v215
	v_cvt_pk_bf16_f32 v29, v29, v29
	ds_write_b16 v179, v29 offset:60672
	v_fma_f32 v29, v139, v18, v215
	v_cvt_pk_bf16_f32 v29, v29, v29
	ds_write_b16 v182, v29 offset:60928
	v_fma_f32 v29, v137, v18, v215
	v_cvt_pk_bf16_f32 v29, v29, v29
	ds_write_b16 v183, v29 offset:61184
	v_fma_f32 v29, v144, v18, v215
	v_cvt_pk_bf16_f32 v29, v29, v29
	ds_write_b16 v184, v29 offset:61440
	v_fma_f32 v29, v142, v18, v215
	v_cvt_pk_bf16_f32 v29, v29, v29
	ds_write_b16 v185, v29 offset:61696
	v_fma_f32 v29, v140, v18, v215
	v_cvt_pk_bf16_f32 v29, v29, v29
	ds_write_b16 v186, v29 offset:61952
	v_fma_f32 v29, v138, v18, v215
	v_cvt_pk_bf16_f32 v29, v29, v29
	ds_write_b16 v187, v29 offset:62208
	v_fma_f32 v29, v133, v18, v215
	v_cvt_pk_bf16_f32 v29, v29, v29
	ds_write_b16 v188, v29 offset:62464
	v_fma_f32 v29, v131, v18, v215
	v_cvt_pk_bf16_f32 v29, v29, v29
	ds_write_b16 v189, v29 offset:62720
	v_fma_f32 v29, v64, v18, v215
	v_cvt_pk_bf16_f32 v29, v29, v29
	ds_write_b16 v190, v29 offset:62976
	v_fma_f32 v29, v62, v18, v215
	v_cvt_pk_bf16_f32 v29, v29, v29
	ds_write_b16 v35, v29 offset:63232
	v_fma_f32 v29, v136, v18, v215
	v_cvt_pk_bf16_f32 v29, v29, v29
	ds_write_b16 v174, v29 offset:63488
	v_fma_f32 v29, v132, v18, v215
	v_cvt_pk_bf16_f32 v29, v29, v29
	ds_write_b16 v175, v29 offset:63744
	v_fma_f32 v29, v65, v18, v215
	v_cvt_pk_bf16_f32 v29, v29, v29
	ds_write_b16 v176, v29 offset:64000
	v_fma_f32 v29, v63, v18, v215
	v_cvt_pk_bf16_f32 v29, v29, v29
	ds_write_b16 v177, v29 offset:64256
	v_fma_f32 v29, v60, v18, v215
	v_cvt_pk_bf16_f32 v29, v29, v29
	ds_write_b16 v178, v29 offset:64512
	v_fma_f32 v29, v59, v18, v215
	v_cvt_pk_bf16_f32 v29, v29, v29
	ds_write_b16 v179, v29 offset:64768
	v_fma_f32 v29, v57, v18, v215
	v_cvt_pk_bf16_f32 v29, v29, v29
	ds_write_b16 v182, v29 offset:65024
	v_fma_f32 v29, v55, v18, v215
	v_cvt_pk_bf16_f32 v29, v29, v29
	ds_write_b16 v183, v29 offset:65280
	v_fma_f32 v29, v61, v18, v215
	v_cvt_pk_bf16_f32 v29, v29, v29
	v_add3_u32 v35, v38, v168, v27
	ds_write_b16 v35, v29 offset:10240
	v_fma_f32 v29, v58, v18, v215
	v_cvt_pk_bf16_f32 v29, v29, v29
	v_add3_u32 v55, v38, v166, v27
	ds_write_b16 v55, v29 offset:10496
	v_fma_f32 v29, v56, v18, v215
	v_cvt_pk_bf16_f32 v29, v29, v29
	v_add3_u32 v56, v38, v164, v27
	ds_write_b16 v56, v29 offset:10752
	v_fma_f32 v29, v54, v18, v215
	v_cvt_pk_bf16_f32 v29, v29, v29
	v_add3_u32 v54, v38, v153, v27
	ds_write_b16 v54, v29 offset:11008
	v_fma_f32 v29, v53, v18, v215
	v_cvt_pk_bf16_f32 v29, v29, v29
	v_add3_u32 v53, v38, v152, v27
	ds_write_b16 v53, v29 offset:11264
	v_fma_f32 v29, v51, v18, v215
	v_cvt_pk_bf16_f32 v29, v29, v29
	v_add3_u32 v51, v38, v151, v27
	ds_write_b16 v51, v29 offset:11520
	v_fma_f32 v29, v49, v18, v215
	v_cvt_pk_bf16_f32 v29, v29, v29
	v_add3_u32 v49, v38, v148, v27
	ds_write_b16 v49, v29 offset:11776
	v_fma_f32 v29, v47, v18, v215
	v_cvt_pk_bf16_f32 v29, v29, v29
	v_add3_u32 v45, v38, v45, v27
	ds_write_b16 v45, v29 offset:12032
	v_fma_f32 v29, v52, v18, v215
	v_cvt_pk_bf16_f32 v29, v29, v29
	v_add3_u32 v46, v38, v46, v27
	ds_write_b16 v46, v29 offset:12288
	v_fma_f32 v29, v50, v18, v215
	v_cvt_pk_bf16_f32 v29, v29, v29
	v_add3_u32 v46, v38, v173, v27
	ds_write_b16 v46, v29 offset:12544
	v_fma_f32 v29, v48, v18, v215
	v_cvt_pk_bf16_f32 v29, v29, v29
	v_add3_u32 v46, v38, v172, v27
	ds_write_b16 v46, v29 offset:12800
	v_mul_f32_e32 v29, v37, v18
	v_bfe_u32 v36, v29, 16, 1
	v_add3_u32 v29, v29, v36, s15
	v_add3_u32 v36, v38, v171, v27
	ds_write_b16_d16_hi v36, v29 offset:13056
	v_fma_f32 v29, v34, v18, v215
	v_cvt_pk_bf16_f32 v29, v29, v29
	v_add3_u32 v34, v38, v170, v27
	ds_write_b16 v34, v29 offset:13312
	v_sub_f32_e32 v29, v24, v39
	v_pk_fma_f32 v[24:25], v[40:41], s[22:23], v[24:25] op_sel_hi:[1,0,1] neg_lo:[1,0,0] neg_hi:[1,0,0]
	v_mul_f32_e32 v29, v29, v18
	v_mul_f32_e32 v24, v25, v18
	v_bfe_u32 v34, v29, 16, 1
	v_bfe_u32 v25, v24, 16, 1
	v_add3_u32 v29, v29, v34, s15
	v_add3_u32 v34, v38, v169, v27
	v_add3_u32 v24, v24, v25, s15
	v_add3_u32 v25, v38, v167, v27
	ds_write_b16_d16_hi v34, v29 offset:13568
	ds_write_b16_d16_hi v25, v24 offset:13824
	v_pk_fma_f32 v[24:25], v[40:41], s[22:23], v[32:33] op_sel_hi:[1,0,1] neg_lo:[1,0,0] neg_hi:[1,0,0]
	v_and_b32_e32 v133, 15, v43
	v_mul_f32_e32 v24, v25, v18
	v_bfe_u32 v25, v24, 16, 1
	v_add3_u32 v24, v24, v25, s15
	v_add3_u32 v25, v38, v165, v27
	ds_write_b16_d16_hi v25, v24 offset:14080
	v_fma_f32 v24, v28, v18, v215
	v_cvt_pk_bf16_f32 v24, v24, v24
	ds_write_b16 v35, v24 offset:14336
	v_sub_f32_e32 v24, v22, v39
	v_pk_fma_f32 v[22:23], v[40:41], s[22:23], v[22:23] op_sel_hi:[1,0,1] neg_lo:[1,0,0] neg_hi:[1,0,0]
	v_mul_f32_e32 v24, v24, v18
	v_mul_f32_e32 v22, v23, v18
	v_bfe_u32 v25, v24, 16, 1
	v_bfe_u32 v23, v22, 16, 1
	v_add3_u32 v24, v24, v25, s15
	v_add3_u32 v22, v22, v23, s15
	ds_write_b16_d16_hi v55, v24 offset:14592
	ds_write_b16_d16_hi v56, v22 offset:14848
	v_pk_fma_f32 v[22:23], v[40:41], s[22:23], v[30:31] op_sel_hi:[1,0,1] neg_lo:[1,0,0] neg_hi:[1,0,0]
	s_nop 0
	v_mul_f32_e32 v22, v23, v18
	v_bfe_u32 v23, v22, 16, 1
	v_add3_u32 v22, v22, v23, s15
	ds_write_b16_d16_hi v54, v22 offset:15104
	v_fma_f32 v22, v26, v18, v215
	v_cvt_pk_bf16_f32 v22, v22, v22
	ds_write_b16 v53, v22 offset:15360
	v_sub_f32_e32 v22, v20, v39
	v_pk_fma_f32 v[20:21], v[40:41], s[22:23], v[20:21] op_sel_hi:[1,0,1] neg_lo:[1,0,0] neg_hi:[1,0,0]
	v_mul_f32_e32 v22, v22, v18
	v_mul_f32_e32 v20, v21, v18
	v_mul_f32_e32 v18, v19, v18
	v_bfe_u32 v23, v22, 16, 1
	v_bfe_u32 v21, v20, 16, 1
	v_bfe_u32 v19, v18, 16, 1
	v_add3_u32 v22, v22, v23, s15
	v_add3_u32 v20, v20, v21, s15
	v_add3_u32 v18, v18, v19, s15
	ds_write_b16_d16_hi v51, v22 offset:15616
	ds_write_b16_d16_hi v49, v20 offset:15872
	ds_write_b16_d16_hi v45, v18 offset:16128
	v_lshrrev_b32_e32 v18, 1, v43
	v_and_b32_e32 v18, 32, v18
	v_lshl_or_b32 v132, v44, 6, v18
	v_or_b32_e32 v18, v132, v134
	v_lshl_add_u32 v131, v18, 8, 32
	v_bitop3_b32 v18, v42, v133, 1 bitop3:0x6c
	v_lshl_add_u32 v18, v18, 4, v131
	v_and_b32_e32 v215, 31, v0
	v_add_u32_e32 v215, s3, v215
	v_lshlrev_b32_e32 v215, 12, v215
	v_and_b32_e32 v245, 0x1c0, v0
	v_add_u32_e32 v215, v215, v245
	v_bfe_u32 v245, v0, 5, 1
	v_lshl_add_u32 v245, v245, 3, v215
	v_bfe_u32 v215, v0, 5, 1
	v_lshl_add_u32 v215, v215, 3, v245
	global_load_dwordx4 v[216:219], v215, s[60:61] offset:3072
	global_load_dwordx4 v[220:223], v215, s[60:61] offset:3104
	s_add_u32 s98, s60, 0x20000
	s_addc_u32 s99, s61, 0
	global_load_dwordx4 v[224:227], v215, s[98:99] offset:3072
	global_load_dwordx4 v[228:231], v215, s[98:99] offset:3104
	s_add_u32 s100, s60, 0x40000
	s_addc_u32 s101, s61, 0
	global_load_dwordx4 v[232:235], v215, s[100:101] offset:3072
	global_load_dwordx4 v[236:239], v215, s[100:101] offset:3104
	s_add_u32 s98, s60, 0x60000
	s_addc_u32 s99, s61, 0
	global_load_dwordx4 v[252:255], v215, s[98:99] offset:3072
	global_load_dwordx2 v[240:241], v245, s[98:99] offset:3104
	global_load_dwordx2 v[246:247], v245, s[98:99] offset:3120
	s_waitcnt lgkmcnt(0)
	s_barrier
	ds_read_b128 v[136:139], v18 offset:55296
	s_waitcnt lgkmcnt(0)
	v_mfma_f32_32x32x16_bf16 v[50:65], v[136:139], v[2:5], 0
	v_mfma_f32_32x32x16_bf16 v[34:49], v[136:139], v[6:9], 0
	v_mfma_f32_32x32x16_bf16 v[18:33], v[136:139], v[10:13], 0
	v_mfma_f32_32x32x16_bf16 v[2:17], v[136:139], v[14:17], 0
	v_bitop3_b32 v136, v135, v133, 2 bitop3:0x36
	v_lshl_add_u32 v136, v136, 4, v131
	ds_read_b128 v[136:139], v136 offset:55296
	s_waitcnt lgkmcnt(0)
	v_mfma_f32_32x32x16_bf16 v[50:65], v[136:139], v[114:117], v[50:65]
	v_bitop3_b32 v114, v135, v133, 4 bitop3:0x36
	v_lshl_add_u32 v114, v114, 4, v131
	ds_read_b128 v[114:117], v114 offset:55296
	v_mfma_f32_32x32x16_bf16 v[34:49], v[136:139], v[118:121], v[34:49]
	v_mfma_f32_32x32x16_bf16 v[18:33], v[136:139], v[122:125], v[18:33]
	s_waitcnt lgkmcnt(0)
	v_mfma_f32_32x32x16_bf16 v[34:49], v[114:117], v[102:105], v[34:49]
	v_bitop3_b32 v102, v135, v133, 6 bitop3:0x36
	v_lshl_add_u32 v102, v102, 4, v131
	ds_read_b128 v[102:105], v102 offset:55296
	v_mfma_f32_32x32x16_bf16 v[2:17], v[136:139], v[126:129], v[2:17]
	v_mfma_f32_32x32x16_bf16 v[18:33], v[114:117], v[106:109], v[18:33]
	s_waitcnt lgkmcnt(0)
	v_mfma_f32_32x32x16_bf16 v[34:49], v[102:105], v[90:93], v[34:49]
	v_bitop3_b32 v90, v135, v133, 8 bitop3:0x36
	v_lshl_add_u32 v90, v90, 4, v131
	ds_read_b128 v[90:93], v90 offset:55296
	v_mfma_f32_32x32x16_bf16 v[2:17], v[114:117], v[110:113], v[2:17]
	v_mfma_f32_32x32x16_bf16 v[18:33], v[102:105], v[94:97], v[18:33]
	v_mfma_f32_32x32x16_bf16 v[2:17], v[102:105], v[98:101], v[2:17]
	v_lshlrev_b32_e32 v104, 7, v130
	v_or_b32_e32 v102, v104, v134
	v_ashrrev_i32_e32 v103, 31, v102
	v_lshlrev_b64 v[106:107], 2, v[102:103]
	v_lshl_or_b32 v98, v135, 2, v132
	v_or_b32_e32 v100, s3, v134
	v_mov_b32_e32 v101, s5
	s_waitcnt lgkmcnt(0)
	v_mfma_f32_32x32x16_bf16 v[18:33], v[90:93], v[82:85], v[18:33]
	v_bitop3_b32 v82, v135, v133, 10 bitop3:0x36
	v_lshl_add_u32 v82, v82, 4, v131
	ds_read_b128 v[82:85], v82 offset:55296
	v_lshl_add_u64 v[108:109], s[6:7], 0, v[106:107]
	v_lshl_add_u64 v[106:107], s[92:93], 0, v[106:107]
	v_ashrrev_i32_e32 v99, 31, v98
	v_lshlrev_b64 v[98:99], 1, v[98:99]
	v_mfma_f32_32x32x16_bf16 v[2:17], v[90:93], v[86:89], v[2:17]
	s_add_i32 s3, s3, s18
	s_cmpk_gt_i32 s4, 0x7f
	s_waitcnt lgkmcnt(0)
	v_mfma_f32_32x32x16_bf16 v[18:33], v[82:85], v[74:77], v[18:33]
	v_bitop3_b32 v74, v135, v133, 12 bitop3:0x36
	v_lshl_add_u32 v74, v74, 4, v131
	ds_read_b128 v[74:77], v74 offset:55296
	v_mfma_f32_32x32x16_bf16 v[2:17], v[82:85], v[78:81], v[2:17]
	s_waitcnt lgkmcnt(0)
	v_mfma_f32_32x32x16_bf16 v[2:17], v[74:77], v[70:73], v[2:17]
	v_bitop3_b32 v70, v135, v133, 14 bitop3:0x36
	v_lshl_add_u32 v70, v70, 4, v131
	ds_read_b128 v[70:73], v70 offset:55296
	v_ashrrev_i32_e32 v133, 31, v132
	s_waitcnt lgkmcnt(0)
	v_mfma_f32_32x32x16_bf16 v[2:17], v[70:73], v[66:69], v[2:17]
	v_lshlrev_b64 v[66:67], 2, v[132:133]
	v_lshl_add_u64 v[68:69], s[10:11], 0, v[66:67]
	v_lshl_add_u64 v[66:67], s[36:37], 0, v[66:67]
	v_lshl_add_u64 v[68:69], v[68:69], 0, v[154:155]
	v_lshl_add_u64 v[70:71], v[66:67], 0, v[154:155]
	global_load_dwordx4 v[90:93], v[68:69], off
	global_load_dwordx4 v[94:97], v[70:71], off
	global_load_dwordx4 v[82:85], v[68:69], off offset:32
	global_load_dwordx4 v[86:89], v[70:71], off offset:32
	global_load_dwordx4 v[74:77], v[68:69], off offset:64
	global_load_dwordx4 v[78:81], v[70:71], off offset:64
	s_nop 0
	global_load_dwordx4 v[66:69], v[68:69], off offset:96
	s_nop 0
	global_load_dwordx4 v[70:73], v[70:71], off offset:96
	s_nop 0
	global_load_dword v118, v[108:109], off
	global_load_dword v119, v[108:109], off offset:128
	global_load_dword v120, v[108:109], off offset:256
	global_load_dword v121, v[108:109], off offset:384
	global_load_dword v122, v[106:107], off
	global_load_dword v123, v[106:107], off offset:128
	global_load_dword v124, v[106:107], off offset:256
	global_load_dword v125, v[106:107], off offset:384
	v_lshlrev_b64 v[110:111], 11, v[100:101]
	v_lshl_add_u64 v[110:111], s[62:63], 0, v[110:111]
	v_lshl_add_u64 v[110:111], v[110:111], 0, v[98:99]
	v_add_co_u32_e32 v112, vcc, 0x10000, v110
	s_nop 1
	v_addc_co_u32_e32 v113, vcc, 0, v111, vcc
	v_add_co_u32_e32 v114, vcc, 0x20000, v110
	s_nop 1
	v_addc_co_u32_e32 v115, vcc, 0, v111, vcc
	v_add_co_u32_e32 v116, vcc, 0x30000, v110
	s_nop 1
	v_addc_co_u32_e32 v117, vcc, 0, v111, vcc
	v_and_b32_e32 v126, 31, v0
	v_lshlrev_b32_e32 v136, 6, v126
	v_bfe_u32 v127, v0, 5, 1
	v_lshl_add_u32 v136, v127, 3, v136
	v_lshrrev_b32_e32 v134, 6, v0
	v_lshl_add_u32 v136, v134, 13, v136
	v_add_u32_e32 v136, 0xd820, v136
	v_bfe_u32 v126, v0, 1, 2
	v_xor_b32_e32 v127, 0, v126
	v_lshl_add_u32 v128, v127, 4, v136
	v_xor_b32_e32 v127, 1, v126
	v_lshl_add_u32 v129, v127, 4, v136
	v_xor_b32_e32 v127, 2, v126
	v_lshl_add_u32 v130, v127, 4, v136
	v_xor_b32_e32 v127, 3, v126
	v_lshl_add_u32 v131, v127, 4, v136
	v_bfe_u32 v135, v0, 2, 4
	v_lshlrev_b32_e32 v132, 6, v135
	v_and_b32_e32 v127, 3, v0
	v_bfe_u32 v126, v0, 3, 2
	v_xor_b32_e32 v126, v127, v126
	v_lshl_add_u32 v132, v126, 4, v132
	v_lshl_add_u32 v132, v134, 13, v132
	v_add_u32_e32 v132, 0xd820, v132
	v_and_b32_e32 v133, -32, v100
	v_add_u32_e32 v133, v133, v135
	v_lshlrev_b32_e32 v133, 11, v133
	v_lshl_add_u32 v133, v134, 6, v133
	v_lshl_add_u32 v133, v127, 4, v133
	s_waitcnt vmcnt(0)
	s_nop 1
	v_permlane32_swap_b32 v216, v218
	v_permlane32_swap_b32 v217, v219
	v_permlane32_swap_b32 v220, v222
	v_permlane32_swap_b32 v221, v223
	v_permlane32_swap_b32 v224, v226
	v_permlane32_swap_b32 v225, v227
	v_permlane32_swap_b32 v228, v230
	v_permlane32_swap_b32 v229, v231
	v_permlane32_swap_b32 v232, v234
	v_permlane32_swap_b32 v233, v235
	v_permlane32_swap_b32 v236, v238
	v_permlane32_swap_b32 v237, v239
	v_permlane32_swap_b32 v252, v254
	v_permlane32_swap_b32 v253, v255
	v_mul_f32_e32 v126, v94, v118
	v_fmac_f32_e32 v126, v50, v90
	v_add_f32_e32 v50, v122, v126
	v_lshlrev_b32_e32 v127, 16, v216
	v_mul_f32_e32 v50, v50, v127
	v_mul_f32_e32 v126, v95, v118
	v_fmac_f32_e32 v126, v51, v91
	v_add_f32_e32 v51, v122, v126
	v_and_b32_e32 v127, 0xffff0000, v216
	v_mul_f32_e32 v51, v51, v127
	v_mul_f32_e32 v126, v96, v118
	v_fmac_f32_e32 v126, v52, v92
	v_add_f32_e32 v52, v122, v126
	v_lshlrev_b32_e32 v127, 16, v217
	v_mul_f32_e32 v52, v52, v127
	v_mul_f32_e32 v126, v97, v118
	v_fmac_f32_e32 v126, v53, v93
	v_add_f32_e32 v53, v122, v126
	v_and_b32_e32 v127, 0xffff0000, v217
	v_mul_f32_e32 v53, v53, v127
	v_cvt_pk_bf16_f32 v50, v50, v51
	v_cvt_pk_bf16_f32 v51, v52, v53
	ds_write_b64 v128, v[50:51] offset:0
	v_mul_f32_e32 v126, v86, v118
	v_fmac_f32_e32 v126, v54, v82
	v_add_f32_e32 v54, v122, v126
	v_lshlrev_b32_e32 v127, 16, v218
	v_mul_f32_e32 v54, v54, v127
	v_mul_f32_e32 v126, v87, v118
	v_fmac_f32_e32 v126, v55, v83
	v_add_f32_e32 v55, v122, v126
	v_and_b32_e32 v127, 0xffff0000, v218
	v_mul_f32_e32 v55, v55, v127
	v_mul_f32_e32 v126, v88, v118
	v_fmac_f32_e32 v126, v56, v84
	v_add_f32_e32 v56, v122, v126
	v_lshlrev_b32_e32 v127, 16, v219
	v_mul_f32_e32 v56, v56, v127
	v_mul_f32_e32 v126, v89, v118
	v_fmac_f32_e32 v126, v57, v85
	v_add_f32_e32 v57, v122, v126
	v_and_b32_e32 v127, 0xffff0000, v219
	v_mul_f32_e32 v57, v57, v127
	v_cvt_pk_bf16_f32 v54, v54, v55
	v_cvt_pk_bf16_f32 v55, v56, v57
	ds_write_b64 v129, v[54:55] offset:0
	v_mul_f32_e32 v126, v78, v118
	v_fmac_f32_e32 v126, v58, v74
	v_add_f32_e32 v58, v122, v126
	v_lshlrev_b32_e32 v127, 16, v220
	v_mul_f32_e32 v58, v58, v127
	v_mul_f32_e32 v126, v79, v118
	v_fmac_f32_e32 v126, v59, v75
	v_add_f32_e32 v59, v122, v126
	v_and_b32_e32 v127, 0xffff0000, v220
	v_mul_f32_e32 v59, v59, v127
	v_mul_f32_e32 v126, v80, v118
	v_fmac_f32_e32 v126, v60, v76
	v_add_f32_e32 v60, v122, v126
	v_lshlrev_b32_e32 v127, 16, v221
	v_mul_f32_e32 v60, v60, v127
	v_mul_f32_e32 v126, v81, v118
	v_fmac_f32_e32 v126, v61, v77
	v_add_f32_e32 v61, v122, v126
	v_and_b32_e32 v127, 0xffff0000, v221
	v_mul_f32_e32 v61, v61, v127
	v_cvt_pk_bf16_f32 v58, v58, v59
	v_cvt_pk_bf16_f32 v59, v60, v61
	ds_write_b64 v130, v[58:59] offset:0
	v_mul_f32_e32 v126, v70, v118
	v_fmac_f32_e32 v126, v62, v66
	v_add_f32_e32 v62, v122, v126
	v_lshlrev_b32_e32 v127, 16, v222
	v_mul_f32_e32 v62, v62, v127
	v_mul_f32_e32 v126, v71, v118
	v_fmac_f32_e32 v126, v63, v67
	v_add_f32_e32 v63, v122, v126
	v_and_b32_e32 v127, 0xffff0000, v222
	v_mul_f32_e32 v63, v63, v127
	v_mul_f32_e32 v126, v72, v118
	v_fmac_f32_e32 v126, v64, v68
	v_add_f32_e32 v64, v122, v126
	v_lshlrev_b32_e32 v127, 16, v223
	v_mul_f32_e32 v64, v64, v127
	v_mul_f32_e32 v126, v73, v118
	v_fmac_f32_e32 v126, v65, v69
	v_add_f32_e32 v65, v122, v126
	v_and_b32_e32 v127, 0xffff0000, v223
	v_mul_f32_e32 v65, v65, v127
	v_cvt_pk_bf16_f32 v62, v62, v63
	v_cvt_pk_bf16_f32 v63, v64, v65
	ds_write_b64 v131, v[62:63] offset:0
	v_mul_f32_e32 v126, v94, v119
	v_fmac_f32_e32 v126, v34, v90
	v_add_f32_e32 v34, v123, v126
	v_lshlrev_b32_e32 v127, 16, v224
	v_mul_f32_e32 v34, v34, v127
	v_mul_f32_e32 v126, v95, v119
	v_fmac_f32_e32 v126, v35, v91
	v_add_f32_e32 v35, v123, v126
	v_and_b32_e32 v127, 0xffff0000, v224
	v_mul_f32_e32 v35, v35, v127
	v_mul_f32_e32 v126, v96, v119
	v_fmac_f32_e32 v126, v36, v92
	v_add_f32_e32 v36, v123, v126
	v_lshlrev_b32_e32 v127, 16, v225
	v_mul_f32_e32 v36, v36, v127
	v_mul_f32_e32 v126, v97, v119
	v_fmac_f32_e32 v126, v37, v93
	v_add_f32_e32 v37, v123, v126
	v_and_b32_e32 v127, 0xffff0000, v225
	v_mul_f32_e32 v37, v37, v127
	v_cvt_pk_bf16_f32 v34, v34, v35
	v_cvt_pk_bf16_f32 v35, v36, v37
	ds_write_b64 v128, v[34:35] offset:2048
	v_mul_f32_e32 v126, v86, v119
	v_fmac_f32_e32 v126, v38, v82
	v_add_f32_e32 v38, v123, v126
	v_lshlrev_b32_e32 v127, 16, v226
	v_mul_f32_e32 v38, v38, v127
	v_mul_f32_e32 v126, v87, v119
	v_fmac_f32_e32 v126, v39, v83
	v_add_f32_e32 v39, v123, v126
	v_and_b32_e32 v127, 0xffff0000, v226
	v_mul_f32_e32 v39, v39, v127
	v_mul_f32_e32 v126, v88, v119
	v_fmac_f32_e32 v126, v40, v84
	v_add_f32_e32 v40, v123, v126
	v_lshlrev_b32_e32 v127, 16, v227
	v_mul_f32_e32 v40, v40, v127
	v_mul_f32_e32 v126, v89, v119
	v_fmac_f32_e32 v126, v41, v85
	v_add_f32_e32 v41, v123, v126
	v_and_b32_e32 v127, 0xffff0000, v227
	v_mul_f32_e32 v41, v41, v127
	v_cvt_pk_bf16_f32 v38, v38, v39
	v_cvt_pk_bf16_f32 v39, v40, v41
	ds_write_b64 v129, v[38:39] offset:2048
	v_mul_f32_e32 v126, v78, v119
	v_fmac_f32_e32 v126, v42, v74
	v_add_f32_e32 v42, v123, v126
	v_lshlrev_b32_e32 v127, 16, v228
	v_mul_f32_e32 v42, v42, v127
	v_mul_f32_e32 v126, v79, v119
	v_fmac_f32_e32 v126, v43, v75
	v_add_f32_e32 v43, v123, v126
	v_and_b32_e32 v127, 0xffff0000, v228
	v_mul_f32_e32 v43, v43, v127
	v_mul_f32_e32 v126, v80, v119
	v_fmac_f32_e32 v126, v44, v76
	v_add_f32_e32 v44, v123, v126
	v_lshlrev_b32_e32 v127, 16, v229
	v_mul_f32_e32 v44, v44, v127
	v_mul_f32_e32 v126, v81, v119
	v_fmac_f32_e32 v126, v45, v77
	v_add_f32_e32 v45, v123, v126
	v_and_b32_e32 v127, 0xffff0000, v229
	v_mul_f32_e32 v45, v45, v127
	v_cvt_pk_bf16_f32 v42, v42, v43
	v_cvt_pk_bf16_f32 v43, v44, v45
	ds_write_b64 v130, v[42:43] offset:2048
	v_mul_f32_e32 v126, v70, v119
	v_fmac_f32_e32 v126, v46, v66
	v_add_f32_e32 v46, v123, v126
	v_lshlrev_b32_e32 v127, 16, v230
	v_mul_f32_e32 v46, v46, v127
	v_mul_f32_e32 v126, v71, v119
	v_fmac_f32_e32 v126, v47, v67
	v_add_f32_e32 v47, v123, v126
	v_and_b32_e32 v127, 0xffff0000, v230
	v_mul_f32_e32 v47, v47, v127
	v_mul_f32_e32 v126, v72, v119
	v_fmac_f32_e32 v126, v48, v68
	v_add_f32_e32 v48, v123, v126
	v_lshlrev_b32_e32 v127, 16, v231
	v_mul_f32_e32 v48, v48, v127
	v_mul_f32_e32 v126, v73, v119
	v_fmac_f32_e32 v126, v49, v69
	v_add_f32_e32 v49, v123, v126
	v_and_b32_e32 v127, 0xffff0000, v231
	v_mul_f32_e32 v49, v49, v127
	v_cvt_pk_bf16_f32 v46, v46, v47
	v_cvt_pk_bf16_f32 v47, v48, v49
	ds_write_b64 v131, v[46:47] offset:2048
	v_mul_f32_e32 v126, v94, v120
	v_fmac_f32_e32 v126, v18, v90
	v_add_f32_e32 v18, v124, v126
	v_lshlrev_b32_e32 v127, 16, v232
	v_mul_f32_e32 v18, v18, v127
	v_mul_f32_e32 v126, v95, v120
	v_fmac_f32_e32 v126, v19, v91
	v_add_f32_e32 v19, v124, v126
	v_and_b32_e32 v127, 0xffff0000, v232
	v_mul_f32_e32 v19, v19, v127
	v_mul_f32_e32 v126, v96, v120
	v_fmac_f32_e32 v126, v20, v92
	v_add_f32_e32 v20, v124, v126
	v_lshlrev_b32_e32 v127, 16, v233
	v_mul_f32_e32 v20, v20, v127
	v_mul_f32_e32 v126, v97, v120
	v_fmac_f32_e32 v126, v21, v93
	v_add_f32_e32 v21, v124, v126
	v_and_b32_e32 v127, 0xffff0000, v233
	v_mul_f32_e32 v21, v21, v127
	v_cvt_pk_bf16_f32 v18, v18, v19
	v_cvt_pk_bf16_f32 v19, v20, v21
	ds_write_b64 v128, v[18:19] offset:4096
	v_mul_f32_e32 v126, v86, v120
	v_fmac_f32_e32 v126, v22, v82
	v_add_f32_e32 v22, v124, v126
	v_lshlrev_b32_e32 v127, 16, v234
	v_mul_f32_e32 v22, v22, v127
	v_mul_f32_e32 v126, v87, v120
	v_fmac_f32_e32 v126, v23, v83
	v_add_f32_e32 v23, v124, v126
	v_and_b32_e32 v127, 0xffff0000, v234
	v_mul_f32_e32 v23, v23, v127
	v_mul_f32_e32 v126, v88, v120
	v_fmac_f32_e32 v126, v24, v84
	v_add_f32_e32 v24, v124, v126
	v_lshlrev_b32_e32 v127, 16, v235
	v_mul_f32_e32 v24, v24, v127
	v_mul_f32_e32 v126, v89, v120
	v_fmac_f32_e32 v126, v25, v85
	v_add_f32_e32 v25, v124, v126
	v_and_b32_e32 v127, 0xffff0000, v235
	v_mul_f32_e32 v25, v25, v127
	v_cvt_pk_bf16_f32 v22, v22, v23
	v_cvt_pk_bf16_f32 v23, v24, v25
	ds_write_b64 v129, v[22:23] offset:4096
	v_mul_f32_e32 v126, v78, v120
	v_fmac_f32_e32 v126, v26, v74
	v_add_f32_e32 v26, v124, v126
	v_lshlrev_b32_e32 v127, 16, v236
	v_mul_f32_e32 v26, v26, v127
	v_mul_f32_e32 v126, v79, v120
	v_fmac_f32_e32 v126, v27, v75
	v_add_f32_e32 v27, v124, v126
	v_and_b32_e32 v127, 0xffff0000, v236
	v_mul_f32_e32 v27, v27, v127
	v_mul_f32_e32 v126, v80, v120
	v_fmac_f32_e32 v126, v28, v76
	v_add_f32_e32 v28, v124, v126
	v_lshlrev_b32_e32 v127, 16, v237
	v_mul_f32_e32 v28, v28, v127
	v_mul_f32_e32 v126, v81, v120
	v_fmac_f32_e32 v126, v29, v77
	v_add_f32_e32 v29, v124, v126
	v_and_b32_e32 v127, 0xffff0000, v237
	v_mul_f32_e32 v29, v29, v127
	v_cvt_pk_bf16_f32 v26, v26, v27
	v_cvt_pk_bf16_f32 v27, v28, v29
	ds_write_b64 v130, v[26:27] offset:4096
	v_mul_f32_e32 v126, v70, v120
	v_fmac_f32_e32 v126, v30, v66
	v_add_f32_e32 v30, v124, v126
	v_lshlrev_b32_e32 v127, 16, v238
	v_mul_f32_e32 v30, v30, v127
	v_mul_f32_e32 v126, v71, v120
	v_fmac_f32_e32 v126, v31, v67
	v_add_f32_e32 v31, v124, v126
	v_and_b32_e32 v127, 0xffff0000, v238
	v_mul_f32_e32 v31, v31, v127
	v_mul_f32_e32 v126, v72, v120
	v_fmac_f32_e32 v126, v32, v68
	v_add_f32_e32 v32, v124, v126
	v_lshlrev_b32_e32 v127, 16, v239
	v_mul_f32_e32 v32, v32, v127
	v_mul_f32_e32 v126, v73, v120
	v_fmac_f32_e32 v126, v33, v69
	v_add_f32_e32 v33, v124, v126
	v_and_b32_e32 v127, 0xffff0000, v239
	v_mul_f32_e32 v33, v33, v127
	v_cvt_pk_bf16_f32 v30, v30, v31
	v_cvt_pk_bf16_f32 v31, v32, v33
	ds_write_b64 v131, v[30:31] offset:4096
	v_mul_f32_e32 v126, v94, v121
	v_fmac_f32_e32 v126, v2, v90
	v_add_f32_e32 v2, v125, v126
	v_lshlrev_b32_e32 v127, 16, v252
	v_mul_f32_e32 v2, v2, v127
	v_mul_f32_e32 v126, v95, v121
	v_fmac_f32_e32 v126, v3, v91
	v_add_f32_e32 v3, v125, v126
	v_and_b32_e32 v127, 0xffff0000, v252
	v_mul_f32_e32 v3, v3, v127
	v_mul_f32_e32 v126, v96, v121
	v_fmac_f32_e32 v126, v4, v92
	v_add_f32_e32 v4, v125, v126
	v_lshlrev_b32_e32 v127, 16, v253
	v_mul_f32_e32 v4, v4, v127
	v_mul_f32_e32 v126, v97, v121
	v_fmac_f32_e32 v126, v5, v93
	v_add_f32_e32 v5, v125, v126
	v_and_b32_e32 v127, 0xffff0000, v253
	v_mul_f32_e32 v5, v5, v127
	v_cvt_pk_bf16_f32 v2, v2, v3
	v_cvt_pk_bf16_f32 v3, v4, v5
	ds_write_b64 v128, v[2:3] offset:6144
	v_mul_f32_e32 v126, v86, v121
	v_fmac_f32_e32 v126, v6, v82
	v_add_f32_e32 v6, v125, v126
	v_lshlrev_b32_e32 v127, 16, v254
	v_mul_f32_e32 v6, v6, v127
	v_mul_f32_e32 v126, v87, v121
	v_fmac_f32_e32 v126, v7, v83
	v_add_f32_e32 v7, v125, v126
	v_and_b32_e32 v127, 0xffff0000, v254
	v_mul_f32_e32 v7, v7, v127
	v_mul_f32_e32 v126, v88, v121
	v_fmac_f32_e32 v126, v8, v84
	v_add_f32_e32 v8, v125, v126
	v_lshlrev_b32_e32 v127, 16, v255
	v_mul_f32_e32 v8, v8, v127
	v_mul_f32_e32 v126, v89, v121
	v_fmac_f32_e32 v126, v9, v85
	v_add_f32_e32 v9, v125, v126
	v_and_b32_e32 v127, 0xffff0000, v255
	v_mul_f32_e32 v9, v9, v127
	v_cvt_pk_bf16_f32 v6, v6, v7
	v_cvt_pk_bf16_f32 v7, v8, v9
	ds_write_b64 v129, v[6:7] offset:6144
	v_mul_f32_e32 v126, v78, v121
	v_fmac_f32_e32 v126, v10, v74
	v_add_f32_e32 v10, v125, v126
	v_lshlrev_b32_e32 v127, 16, v240
	v_mul_f32_e32 v10, v10, v127
	v_mul_f32_e32 v126, v79, v121
	v_fmac_f32_e32 v126, v11, v75
	v_add_f32_e32 v11, v125, v126
	v_and_b32_e32 v127, 0xffff0000, v240
	v_mul_f32_e32 v11, v11, v127
	v_mul_f32_e32 v126, v80, v121
	v_fmac_f32_e32 v126, v12, v76
	v_add_f32_e32 v12, v125, v126
	v_lshlrev_b32_e32 v127, 16, v241
	v_mul_f32_e32 v12, v12, v127
	v_mul_f32_e32 v126, v81, v121
	v_fmac_f32_e32 v126, v13, v77
	v_add_f32_e32 v13, v125, v126
	v_and_b32_e32 v127, 0xffff0000, v241
	v_mul_f32_e32 v13, v13, v127
	v_cvt_pk_bf16_f32 v10, v10, v11
	v_cvt_pk_bf16_f32 v11, v12, v13
	ds_write_b64 v130, v[10:11] offset:6144
	v_mul_f32_e32 v126, v70, v121
	v_fmac_f32_e32 v126, v14, v66
	v_add_f32_e32 v14, v125, v126
	v_lshlrev_b32_e32 v127, 16, v246
	v_mul_f32_e32 v14, v14, v127
	v_mul_f32_e32 v126, v71, v121
	v_fmac_f32_e32 v126, v15, v67
	v_add_f32_e32 v15, v125, v126
	v_and_b32_e32 v127, 0xffff0000, v246
	v_mul_f32_e32 v15, v15, v127
	v_mul_f32_e32 v126, v72, v121
	v_fmac_f32_e32 v126, v16, v68
	v_add_f32_e32 v16, v125, v126
	v_lshlrev_b32_e32 v127, 16, v247
	v_mul_f32_e32 v16, v16, v127
	v_mul_f32_e32 v126, v73, v121
	v_fmac_f32_e32 v126, v17, v69
	v_add_f32_e32 v17, v125, v126
	v_and_b32_e32 v127, 0xffff0000, v247
	v_mul_f32_e32 v17, v17, v127
	v_cvt_pk_bf16_f32 v14, v14, v15
	v_cvt_pk_bf16_f32 v15, v16, v17
	ds_write_b64 v131, v[14:15] offset:6144
	s_waitcnt lgkmcnt(0)
	ds_read_b128 v[2:5], v132 offset:0
	ds_read_b128 v[6:9], v132 offset:1024
	ds_read_b128 v[10:13], v132 offset:2048
	ds_read_b128 v[14:17], v132 offset:3072
	ds_read_b128 v[18:21], v132 offset:4096
	ds_read_b128 v[22:25], v132 offset:5120
	ds_read_b128 v[26:29], v132 offset:6144
	ds_read_b128 v[30:33], v132 offset:7168
	s_waitcnt lgkmcnt(7)
	global_store_dwordx4 v133, v[2:5], s[62:63] offset:1536
	v_add_u32_e32 v127, 0x8000, v133
	s_waitcnt lgkmcnt(6)
	global_store_dwordx4 v127, v[6:9], s[62:63] offset:1536
	v_add_u32_e32 v126, 0x10000, v133
	s_waitcnt lgkmcnt(5)
	global_store_dwordx4 v126, v[10:13], s[62:63] offset:1536
	v_add_u32_e32 v127, 0x18000, v133
	s_waitcnt lgkmcnt(4)
	global_store_dwordx4 v127, v[14:17], s[62:63] offset:1536
	v_add_u32_e32 v126, 0x20000, v133
	s_waitcnt lgkmcnt(3)
	global_store_dwordx4 v126, v[18:21], s[62:63] offset:1536
	v_add_u32_e32 v127, 0x28000, v133
	s_waitcnt lgkmcnt(2)
	global_store_dwordx4 v127, v[22:25], s[62:63] offset:1536
	v_add_u32_e32 v126, 0x30000, v133
	s_waitcnt lgkmcnt(1)
	global_store_dwordx4 v126, v[26:29], s[62:63] offset:1536
	v_add_u32_e32 v127, 0x38000, v133
	s_waitcnt lgkmcnt(0)
	global_store_dwordx4 v127, v[30:33], s[62:63] offset:1536
	s_barrier
	s_cbranch_scc0 .LBB0_849
